# removed the back-to-back s_setprio 0/1 pair in the middle of each 32-MFMA phase
# baseline (speedup 1.0000x reference)
; #define PG8_STAGE(bufoff, gbase, voff) do { _Pragma("unroll") for (int _i = 0; _i < 2; ++_i) \
;         __builtin_amdgcn_global_load_lds((const unsigned*)((const char*)(gbase) + (voff)[_i]), (LAS unsigned*)(lds + (bufoff) + ldsw + _i * 8192), 16, 0, 0); } while (0)
; #define PG8_LDA(dst, b, h) do { _Pragma("unroll") for (int m = 0; m < 4; ++m) _Pragma("unroll") for (int k = 0; k < 2; ++k) dst[m][k] = *(const LAS bf16x8*)(lds + PG8_SA(b, h) + aoff + m * 2048 + k * 1024); } while (0)
; #define PG8_LDB(dst, b, h) do { _Pragma("unroll") for (int n = 0; n < 2; ++n) _Pragma("unroll") for (int k = 0; k < 2; ++k) dst[n][k] = *(const LAS bf16x8*)(lds + PG8_SB(b, h) + boff + n * 2048 + k * 1024); } while (0)
; #define PG8_MMA(ai, bj, At, Bt) do { __builtin_amdgcn_s_setprio(1); _Pragma("unroll") for (int m = 0; m < 4; ++m) _Pragma("unroll") for (int n = 0; n < 2; ++n) _Pragma("unroll") for (int k = 0; k < 2; ++k) \
;         acc[ai][bj][m][n] = __builtin_amdgcn_mfma_f32_16x16x32_bf16(Bt[n][k], At[m][k], acc[ai][bj][m][n], 0, 0, 0); __builtin_amdgcn_s_setprio(0); } while (0)
; #define PG8_WAIT_V(n) asm volatile("s_waitcnt vmcnt(" #n ")" ::: "memory")
; #define PG8_WAIT_L(n) asm volatile("s_waitcnt lgkmcnt(" #n ")" ::: "memory")
; template <class Epi, class Sched, bool APERM = false, bool HALFN = false>
; __device__ __forceinline__ void gemm_phase(LAS unsigned char* lds, const int tid_in, const int K, const Sched& S, const Epi& E) {
;     ...
;         for (int t = 0; t < nt; t += 2) {
;             const bool last = (t == nt - 2);
;             const char* a1 = cA + (size_t)(t + 1) * kstep;
;             const char* a2 = last ? nA : cA + (size_t)(t + 2) * kstep; const char* b2 = last ? nB : cB + (size_t)(t + 2) * kstep;
;             const char* a3 = a2 + kstep; const char* b3 = b2 + kstep;
;             PG8_LDB(B0, 0, 0); PG8_LDB(B1, 0, 1); PG8_SCHED; PG8_LDA(At, 0, 0); PG8_STAGE(PG8_SA(1, 1), a1 + hstepA, voffA);
;             PG8_WAIT_V(8); PG8_WAIT_L(0); PG8_BAR; PG8_MMA(0, 0, At, B0); if constexpr (!HALFN) PG8_MMA(0, 1, At, B1); PG8_BAR; PG8_SCHED;
;             PG8_LDA(At, 0, 1); PG8_STAGE(PG8_SB(0, 0), b2, voffB); PG8_STAGE(PG8_SB(0, 1), b2 + hstep, voffB); PG8_STAGE(PG8_SA(0, 0), a2, voffA);
;             PG8_WAIT_V(8); PG8_WAIT_L(0); PG8_BAR; PG8_MMA(1, 0, At, B0); if constexpr (!HALFN) PG8_MMA(1, 1, At, B1); PG8_BAR; PG8_SCHED;
.LBB0_346:
	s_add_u32 s4, s0, 0xfff80080
	s_addc_u32 s5, s1, -1
	s_add_i32 s44, 0, 0x10000
	s_cmp_eq_u32 s25, 28
	s_cselect_b32 s17, s19, s5
	s_cselect_b32 s16, s20, s4
	s_cselect_b32 s5, s21, s24
	s_cselect_b32 s4, s22, s23
	s_add_i32 s52, 0, 0x14000
	v_add_u32_e32 v180, s44, v139
	v_add_u32_e32 v196, s52, v139
	ds_read_b128 v[168:171], v180
	ds_read_b128 v[172:175], v180 offset:1024
	ds_read_b128 v[176:179], v180 offset:2048
	ds_read_b128 v[180:183], v180 offset:3072
	ds_read_b128 v[184:187], v196
	ds_read_b128 v[188:191], v196 offset:1024
	ds_read_b128 v[192:195], v196 offset:2048
	ds_read_b128 v[196:199], v196 offset:3072
	v_lshl_add_u64 v[232:233], s[0:1], 0, v[166:167]
	s_add_i32 m0, s38, 0xc000
	ds_read_b128 v[204:207], v141
	ds_read_b128 v[208:211], v141 offset:1024
	ds_read_b128 v[212:215], v141 offset:2048
	ds_read_b128 v[216:219], v141 offset:3072
	ds_read_b128 v[220:223], v141 offset:4096
	ds_read_b128 v[224:227], v141 offset:5120
	ds_read_b128 v[228:231], v141 offset:6144
	ds_read_b128 v[244:247], v141 offset:7168
	global_load_lds_dwordx4 v[232:233], off
	v_lshl_add_u64 v[232:233], s[0:1], 0, v[164:165]
	s_add_i32 m0, s38, 0xe000
	s_nop 0
	global_load_lds_dwordx4 v[232:233], off
	s_waitcnt vmcnt(8)
	s_waitcnt lgkmcnt(0)
	s_barrier
	s_setprio 1
	s_waitcnt lgkmcnt(0)
	v_mfma_f32_16x16x32_bf16 v[124:127], v[168:171], v[204:207], v[124:127]
	v_mfma_f32_16x16x32_bf16 v[120:123], v[176:179], v[204:207], v[120:123]
	v_mfma_f32_16x16x32_bf16 v[108:111], v[168:171], v[212:215], v[108:111]
	v_mfma_f32_16x16x32_bf16 v[104:107], v[176:179], v[212:215], v[104:107]
	v_mfma_f32_16x16x32_bf16 v[92:95], v[168:171], v[220:223], v[92:95]
	v_mfma_f32_16x16x32_bf16 v[88:91], v[176:179], v[220:223], v[88:91]
	v_mfma_f32_16x16x32_bf16 v[76:79], v[168:171], v[228:231], v[76:79]
	v_mfma_f32_16x16x32_bf16 v[72:75], v[176:179], v[228:231], v[72:75]
	v_mfma_f32_16x16x32_bf16 v[124:127], v[172:175], v[208:211], v[124:127]
	v_mfma_f32_16x16x32_bf16 v[120:123], v[180:183], v[208:211], v[120:123]
	v_mfma_f32_16x16x32_bf16 v[108:111], v[172:175], v[216:219], v[108:111]
	v_mfma_f32_16x16x32_bf16 v[104:107], v[180:183], v[216:219], v[104:107]
	v_mfma_f32_16x16x32_bf16 v[92:95], v[172:175], v[224:227], v[92:95]
	v_mfma_f32_16x16x32_bf16 v[88:91], v[180:183], v[224:227], v[88:91]
	v_mfma_f32_16x16x32_bf16 v[76:79], v[172:175], v[244:247], v[76:79]
	v_mfma_f32_16x16x32_bf16 v[72:75], v[180:183], v[244:247], v[72:75]
	v_mfma_f32_16x16x32_bf16 v[116:119], v[184:187], v[204:207], v[116:119]
	v_mfma_f32_16x16x32_bf16 v[112:115], v[192:195], v[204:207], v[112:115]
	v_mfma_f32_16x16x32_bf16 v[100:103], v[184:187], v[212:215], v[100:103]
	v_mfma_f32_16x16x32_bf16 v[96:99], v[192:195], v[212:215], v[96:99]
	v_mfma_f32_16x16x32_bf16 v[84:87], v[184:187], v[220:223], v[84:87]
	v_mfma_f32_16x16x32_bf16 v[80:83], v[192:195], v[220:223], v[80:83]
	v_mfma_f32_16x16x32_bf16 v[68:71], v[184:187], v[228:231], v[68:71]
	v_mfma_f32_16x16x32_bf16 v[64:67], v[192:195], v[228:231], v[64:67]
	v_mfma_f32_16x16x32_bf16 v[116:119], v[188:191], v[208:211], v[116:119]
	v_mfma_f32_16x16x32_bf16 v[112:115], v[196:199], v[208:211], v[112:115]
	v_mfma_f32_16x16x32_bf16 v[100:103], v[188:191], v[216:219], v[100:103]
	v_mfma_f32_16x16x32_bf16 v[96:99], v[196:199], v[216:219], v[96:99]
	v_mfma_f32_16x16x32_bf16 v[84:87], v[188:191], v[224:227], v[84:87]
	v_mfma_f32_16x16x32_bf16 v[80:83], v[196:199], v[224:227], v[80:83]
	v_mfma_f32_16x16x32_bf16 v[68:71], v[188:191], v[244:247], v[68:71]
	v_mfma_f32_16x16x32_bf16 v[64:67], v[196:199], v[244:247], v[64:67]
	s_setprio 0
	s_barrier
	s_add_i32 s44, s44, s35
	v_lshl_add_u64 v[232:233], s[4:5], 0, v[130:131]
	s_mov_b32 m0, s44
	ds_read_b128 v[204:207], v141 offset:16384
	ds_read_b128 v[208:211], v141 offset:17408
	ds_read_b128 v[212:215], v141 offset:18432
	ds_read_b128 v[216:219], v141 offset:19456
	ds_read_b128 v[220:223], v141 offset:20480
	ds_read_b128 v[224:227], v141 offset:21504
	ds_read_b128 v[228:231], v141 offset:22528
	ds_read_b128 v[244:247], v141 offset:23552
	global_load_lds_dwordx4 v[232:233], off
	s_add_i32 m0, s44, 0x2000
	s_add_u32 s44, s4, 0x80000
	v_lshl_add_u64 v[248:249], s[4:5], 0, v[134:135]
	s_addc_u32 s45, s5, 0
	s_add_i32 s52, s52, s35
	global_load_lds_dwordx4 v[248:249], off
	v_lshl_add_u64 v[250:251], s[44:45], 0, v[130:131]
	s_mov_b32 m0, s52
	v_lshl_add_u64 v[252:253], s[16:17], 0, v[132:133]
	global_load_lds_dwordx4 v[250:251], off
	v_lshl_add_u64 v[250:251], s[44:45], 0, v[134:135]
	s_add_i32 m0, s52, 0x2000
	s_nop 0
	global_load_lds_dwordx4 v[250:251], off
	v_lshl_add_u64 v[250:251], s[16:17], 0, v[128:129]
	s_mov_b32 m0, s38
	s_nop 0
	global_load_lds_dwordx4 v[250:251], off
	s_mov_b32 m0, s39
	s_nop 0
	global_load_lds_dwordx4 v[252:253], off
	s_waitcnt vmcnt(8)
	s_waitcnt lgkmcnt(0)
	s_barrier
; #define PG8_STAGE(bufoff, gbase, voff) do { _Pragma("unroll") for (int _i = 0; _i < 2; ++_i) \
;         __builtin_amdgcn_global_load_lds((const unsigned*)((const char*)(gbase) + (voff)[_i]), (LAS unsigned*)(lds + (bufoff) + ldsw + _i * 8192), 16, 0, 0); } while (0)
; #define PG8_LDA(dst, b, h) do { _Pragma("unroll") for (int m = 0; m < 4; ++m) _Pragma("unroll") for (int k = 0; k < 2; ++k) dst[m][k] = *(const LAS bf16x8*)(lds + PG8_SA(b, h) + aoff + m * 2048 + k * 1024); } while (0)
; #define PG8_LDB(dst, b, h) do { _Pragma("unroll") for (int n = 0; n < 2; ++n) _Pragma("unroll") for (int k = 0; k < 2; ++k) dst[n][k] = *(const LAS bf16x8*)(lds + PG8_SB(b, h) + boff + n * 2048 + k * 1024); } while (0)
; #define PG8_MMA(ai, bj, At, Bt) do { __builtin_amdgcn_s_setprio(1); _Pragma("unroll") for (int m = 0; m < 4; ++m) _Pragma("unroll") for (int n = 0; n < 2; ++n) _Pragma("unroll") for (int k = 0; k < 2; ++k) \
;         acc[ai][bj][m][n] = __builtin_amdgcn_mfma_f32_16x16x32_bf16(Bt[n][k], At[m][k], acc[ai][bj][m][n], 0, 0, 0); __builtin_amdgcn_s_setprio(0); } while (0)
; #define PG8_WAIT_V(n) asm volatile("s_waitcnt vmcnt(" #n ")" ::: "memory")
; #define PG8_WAIT_L(n) asm volatile("s_waitcnt lgkmcnt(" #n ")" ::: "memory")
; #define PG8_BAR __builtin_amdgcn_s_barrier()
; #define PG8_SCHED __builtin_amdgcn_sched_barrier(0)
; template <class Epi, class Sched, bool APERM = false, bool HALFN = false>
; __device__ __forceinline__ void gemm_phase(LAS unsigned char* lds, const int tid_in, const int K, const Sched& S, const Epi& E) {
;     ...
;             PG8_WAIT_V(8); PG8_WAIT_L(0); PG8_BAR; PG8_MMA(1, 0, At, B0); if constexpr (!HALFN) PG8_MMA(1, 1, At, B1); PG8_BAR; PG8_SCHED;
;             PG8_LDB(B0, 1, 0); PG8_LDB(B1, 1, 1); PG8_SCHED; PG8_LDA(At, 1, 0); PG8_STAGE(PG8_SA(0, 1), a2 + hstepA, voffA);
;             PG8_WAIT_V(8); PG8_WAIT_L(0); PG8_BAR; PG8_MMA(0, 0, At, B0); if constexpr (!HALFN) PG8_MMA(0, 1, At, B1); PG8_BAR; PG8_SCHED;
;             PG8_LDA(At, 1, 1); PG8_STAGE(PG8_SB(1, 0), b3, voffB); PG8_STAGE(PG8_SB(1, 1), b3 + hstep, voffB); PG8_STAGE(PG8_SA(1, 0), a3, voffA);
	s_setprio 1
	s_waitcnt lgkmcnt(0)
	v_mfma_f32_16x16x32_bf16 v[60:63], v[168:171], v[204:207], v[60:63]
	v_mfma_f32_16x16x32_bf16 v[56:59], v[176:179], v[204:207], v[56:59]
	v_mfma_f32_16x16x32_bf16 v[44:47], v[168:171], v[212:215], v[44:47]
	v_mfma_f32_16x16x32_bf16 v[40:43], v[176:179], v[212:215], v[40:43]
	v_mfma_f32_16x16x32_bf16 v[28:31], v[168:171], v[220:223], v[28:31]
	v_mfma_f32_16x16x32_bf16 v[24:27], v[176:179], v[220:223], v[24:27]
	v_mfma_f32_16x16x32_bf16 v[12:15], v[168:171], v[228:231], v[12:15]
	v_mfma_f32_16x16x32_bf16 v[8:11], v[176:179], v[228:231], v[8:11]
	v_mfma_f32_16x16x32_bf16 v[60:63], v[172:175], v[208:211], v[60:63]
	v_mfma_f32_16x16x32_bf16 v[56:59], v[180:183], v[208:211], v[56:59]
	v_mfma_f32_16x16x32_bf16 v[44:47], v[172:175], v[216:219], v[44:47]
	v_mfma_f32_16x16x32_bf16 v[40:43], v[180:183], v[216:219], v[40:43]
	v_mfma_f32_16x16x32_bf16 v[28:31], v[172:175], v[224:227], v[28:31]
	v_mfma_f32_16x16x32_bf16 v[24:27], v[180:183], v[224:227], v[24:27]
	v_mfma_f32_16x16x32_bf16 v[12:15], v[172:175], v[244:247], v[12:15]
	v_mfma_f32_16x16x32_bf16 v[8:11], v[180:183], v[244:247], v[8:11]
	v_mfma_f32_16x16x32_bf16 v[52:55], v[184:187], v[204:207], v[52:55]
	v_mfma_f32_16x16x32_bf16 v[48:51], v[192:195], v[204:207], v[48:51]
	v_mfma_f32_16x16x32_bf16 v[36:39], v[184:187], v[212:215], v[36:39]
	v_mfma_f32_16x16x32_bf16 v[32:35], v[192:195], v[212:215], v[32:35]
	v_mfma_f32_16x16x32_bf16 v[20:23], v[184:187], v[220:223], v[20:23]
	v_mfma_f32_16x16x32_bf16 v[16:19], v[192:195], v[220:223], v[16:19]
	v_mfma_f32_16x16x32_bf16 v[4:7], v[184:187], v[228:231], v[4:7]
	v_mfma_f32_16x16x32_bf16 v[0:3], v[192:195], v[228:231], v[0:3]
	v_mfma_f32_16x16x32_bf16 v[52:55], v[188:191], v[208:211], v[52:55]
	v_mfma_f32_16x16x32_bf16 v[48:51], v[196:199], v[208:211], v[48:51]
	v_mfma_f32_16x16x32_bf16 v[36:39], v[188:191], v[216:219], v[36:39]
	v_mfma_f32_16x16x32_bf16 v[32:35], v[196:199], v[216:219], v[32:35]
	v_mfma_f32_16x16x32_bf16 v[20:23], v[188:191], v[224:227], v[20:23]
	v_mfma_f32_16x16x32_bf16 v[16:19], v[196:199], v[224:227], v[16:19]
	v_mfma_f32_16x16x32_bf16 v[4:7], v[188:191], v[244:247], v[4:7]
	v_mfma_f32_16x16x32_bf16 v[0:3], v[196:199], v[244:247], v[0:3]
	s_setprio 0
	s_barrier
	s_add_i32 s44, 0, 0x18000
	s_add_i32 s45, 0, 0x1c000
	v_add_u32_e32 v180, s44, v139
	v_add_u32_e32 v196, s45, v139
	ds_read_b128 v[168:171], v180
	ds_read_b128 v[172:175], v180 offset:1024
	ds_read_b128 v[176:179], v180 offset:2048
	ds_read_b128 v[180:183], v180 offset:3072
	ds_read_b128 v[184:187], v196
	ds_read_b128 v[188:191], v196 offset:1024
	ds_read_b128 v[192:195], v196 offset:2048
	ds_read_b128 v[196:199], v196 offset:3072
	s_add_u32 s16, s16, 0x80000
	s_addc_u32 s17, s17, 0
	s_mov_b32 m0, s57
	v_lshl_add_u64 v[236:237], s[16:17], 0, v[128:129]
	ds_read_b128 v[204:207], v141 offset:32768
	ds_read_b128 v[208:211], v141 offset:33792
	ds_read_b128 v[212:215], v141 offset:34816
	ds_read_b128 v[216:219], v141 offset:35840
	ds_read_b128 v[220:223], v141 offset:36864
	ds_read_b128 v[224:227], v141 offset:37888
	ds_read_b128 v[228:231], v141 offset:38912
	ds_read_b128 v[244:247], v141 offset:39936
	global_load_lds_dwordx4 v[236:237], off
	v_lshl_add_u64 v[236:237], s[16:17], 0, v[132:133]
	s_mov_b32 m0, s70
	s_nop 0
	global_load_lds_dwordx4 v[236:237], off
	s_waitcnt vmcnt(8)
	s_waitcnt lgkmcnt(0)
	s_barrier
	s_setprio 1
	s_waitcnt lgkmcnt(0)
	v_mfma_f32_16x16x32_bf16 v[124:127], v[168:171], v[204:207], v[124:127]
	v_mfma_f32_16x16x32_bf16 v[120:123], v[176:179], v[204:207], v[120:123]
	v_mfma_f32_16x16x32_bf16 v[108:111], v[168:171], v[212:215], v[108:111]
	v_mfma_f32_16x16x32_bf16 v[104:107], v[176:179], v[212:215], v[104:107]
	v_mfma_f32_16x16x32_bf16 v[92:95], v[168:171], v[220:223], v[92:95]
	v_mfma_f32_16x16x32_bf16 v[88:91], v[176:179], v[220:223], v[88:91]
	v_mfma_f32_16x16x32_bf16 v[76:79], v[168:171], v[228:231], v[76:79]
	v_mfma_f32_16x16x32_bf16 v[72:75], v[176:179], v[228:231], v[72:75]
	v_mfma_f32_16x16x32_bf16 v[124:127], v[172:175], v[208:211], v[124:127]
	v_mfma_f32_16x16x32_bf16 v[120:123], v[180:183], v[208:211], v[120:123]
	v_mfma_f32_16x16x32_bf16 v[108:111], v[172:175], v[216:219], v[108:111]
	v_mfma_f32_16x16x32_bf16 v[104:107], v[180:183], v[216:219], v[104:107]
	v_mfma_f32_16x16x32_bf16 v[92:95], v[172:175], v[224:227], v[92:95]
	v_mfma_f32_16x16x32_bf16 v[88:91], v[180:183], v[224:227], v[88:91]
	v_mfma_f32_16x16x32_bf16 v[76:79], v[172:175], v[244:247], v[76:79]
	v_mfma_f32_16x16x32_bf16 v[72:75], v[180:183], v[244:247], v[72:75]
	v_mfma_f32_16x16x32_bf16 v[116:119], v[184:187], v[204:207], v[116:119]
	v_mfma_f32_16x16x32_bf16 v[112:115], v[192:195], v[204:207], v[112:115]
	v_mfma_f32_16x16x32_bf16 v[100:103], v[184:187], v[212:215], v[100:103]
	v_mfma_f32_16x16x32_bf16 v[96:99], v[192:195], v[212:215], v[96:99]
	v_mfma_f32_16x16x32_bf16 v[84:87], v[184:187], v[220:223], v[84:87]
	v_mfma_f32_16x16x32_bf16 v[80:83], v[192:195], v[220:223], v[80:83]
	v_mfma_f32_16x16x32_bf16 v[68:71], v[184:187], v[228:231], v[68:71]
	v_mfma_f32_16x16x32_bf16 v[64:67], v[192:195], v[228:231], v[64:67]
	v_mfma_f32_16x16x32_bf16 v[116:119], v[188:191], v[208:211], v[116:119]
	v_mfma_f32_16x16x32_bf16 v[112:115], v[196:199], v[208:211], v[112:115]
	v_mfma_f32_16x16x32_bf16 v[100:103], v[188:191], v[216:219], v[100:103]
	v_mfma_f32_16x16x32_bf16 v[96:99], v[196:199], v[216:219], v[96:99]
	v_mfma_f32_16x16x32_bf16 v[84:87], v[188:191], v[224:227], v[84:87]
	v_mfma_f32_16x16x32_bf16 v[80:83], v[196:199], v[224:227], v[80:83]
	v_mfma_f32_16x16x32_bf16 v[68:71], v[188:191], v[244:247], v[68:71]
	v_mfma_f32_16x16x32_bf16 v[64:67], v[196:199], v[244:247], v[64:67]
	s_setprio 0
	s_barrier
; #define PG8_STAGE(bufoff, gbase, voff) do { _Pragma("unroll") for (int _i = 0; _i < 2; ++_i) \
;         __builtin_amdgcn_global_load_lds((const unsigned*)((const char*)(gbase) + (voff)[_i]), (LAS unsigned*)(lds + (bufoff) + ldsw + _i * 8192), 16, 0, 0); } while (0)
; #define PG8_LDA(dst, b, h) do { _Pragma("unroll") for (int m = 0; m < 4; ++m) _Pragma("unroll") for (int k = 0; k < 2; ++k) dst[m][k] = *(const LAS bf16x8*)(lds + PG8_SA(b, h) + aoff + m * 2048 + k * 1024); } while (0)
; #define PG8_MMA(ai, bj, At, Bt) do { __builtin_amdgcn_s_setprio(1); _Pragma("unroll") for (int m = 0; m < 4; ++m) _Pragma("unroll") for (int n = 0; n < 2; ++n) _Pragma("unroll") for (int k = 0; k < 2; ++k) \
;         acc[ai][bj][m][n] = __builtin_amdgcn_mfma_f32_16x16x32_bf16(Bt[n][k], At[m][k], acc[ai][bj][m][n], 0, 0, 0); __builtin_amdgcn_s_setprio(0); } while (0)
; #define PG8_WAIT_V(n) asm volatile("s_waitcnt vmcnt(" #n ")" ::: "memory")
; #define PG8_WAIT_L(n) asm volatile("s_waitcnt lgkmcnt(" #n ")" ::: "memory")
; #define PG8_BAR __builtin_amdgcn_s_barrier()
; #define PG8_SCHED __builtin_amdgcn_sched_barrier(0)
; template <class Epi, class Sched, bool APERM = false, bool HALFN = false>
; __device__ __forceinline__ void gemm_phase(LAS unsigned char* lds, const int tid_in, const int K, const Sched& S, const Epi& E) {
;     ...
;             PG8_LDA(At, 1, 1); PG8_STAGE(PG8_SB(1, 0), b3, voffB); PG8_STAGE(PG8_SB(1, 1), b3 + hstep, voffB); PG8_STAGE(PG8_SA(1, 0), a3, voffA);
;             PG8_WAIT_V(8); PG8_WAIT_L(0); PG8_BAR; PG8_MMA(1, 0, At, B0); if constexpr (!HALFN) PG8_MMA(1, 1, At, B1); PG8_BAR; PG8_SCHED;
;         }
	s_add_i32 s16, s44, s35
	v_lshl_add_u64 v[232:233], v[232:233], 0, s[78:79]
	s_mov_b32 m0, s16
	ds_read_b128 v[204:207], v141 offset:49152
	ds_read_b128 v[208:211], v141 offset:50176
	ds_read_b128 v[212:215], v141 offset:51200
	ds_read_b128 v[216:219], v141 offset:52224
	ds_read_b128 v[220:223], v141 offset:53248
	ds_read_b128 v[224:227], v141 offset:54272
	ds_read_b128 v[228:231], v141 offset:55296
	ds_read_b128 v[244:247], v141 offset:56320
	global_load_lds_dwordx4 v[232:233], off
	s_add_i32 m0, s16, 0x2000
	s_add_u32 s4, s4, 0x80080
	v_lshl_add_u64 v[232:233], v[248:249], 0, s[78:79]
	s_addc_u32 s5, s5, 0
	s_add_i32 s16, s45, s35
	global_load_lds_dwordx4 v[232:233], off
	v_lshl_add_u64 v[232:233], s[4:5], 0, v[130:131]
	s_mov_b32 m0, s16
	s_nop 0
	global_load_lds_dwordx4 v[232:233], off
	v_lshl_add_u64 v[232:233], s[4:5], 0, v[134:135]
	s_add_i32 m0, s16, 0x2000
	s_nop 0
	global_load_lds_dwordx4 v[232:233], off
	v_lshl_add_u64 v[232:233], v[250:251], 0, s[78:79]
	s_mov_b32 m0, s71
	s_nop 0
	global_load_lds_dwordx4 v[232:233], off
	v_lshl_add_u64 v[232:233], v[252:253], 0, s[78:79]
	s_mov_b32 m0, s74
	s_nop 0
	global_load_lds_dwordx4 v[232:233], off
	s_waitcnt vmcnt(8)
	s_waitcnt lgkmcnt(0)
	s_barrier
	s_setprio 1
	s_waitcnt lgkmcnt(0)
	v_mfma_f32_16x16x32_bf16 v[60:63], v[168:171], v[204:207], v[60:63]
	v_mfma_f32_16x16x32_bf16 v[56:59], v[176:179], v[204:207], v[56:59]
	v_mfma_f32_16x16x32_bf16 v[44:47], v[168:171], v[212:215], v[44:47]
	v_mfma_f32_16x16x32_bf16 v[40:43], v[176:179], v[212:215], v[40:43]
	v_mfma_f32_16x16x32_bf16 v[28:31], v[168:171], v[220:223], v[28:31]
	v_mfma_f32_16x16x32_bf16 v[24:27], v[176:179], v[220:223], v[24:27]
	v_mfma_f32_16x16x32_bf16 v[12:15], v[168:171], v[228:231], v[12:15]
	v_mfma_f32_16x16x32_bf16 v[8:11], v[176:179], v[228:231], v[8:11]
	v_mfma_f32_16x16x32_bf16 v[60:63], v[172:175], v[208:211], v[60:63]
	v_mfma_f32_16x16x32_bf16 v[56:59], v[180:183], v[208:211], v[56:59]
	v_mfma_f32_16x16x32_bf16 v[44:47], v[172:175], v[216:219], v[44:47]
	v_mfma_f32_16x16x32_bf16 v[40:43], v[180:183], v[216:219], v[40:43]
	v_mfma_f32_16x16x32_bf16 v[28:31], v[172:175], v[224:227], v[28:31]
	v_mfma_f32_16x16x32_bf16 v[24:27], v[180:183], v[224:227], v[24:27]
	v_mfma_f32_16x16x32_bf16 v[12:15], v[172:175], v[244:247], v[12:15]
	v_mfma_f32_16x16x32_bf16 v[8:11], v[180:183], v[244:247], v[8:11]
	v_mfma_f32_16x16x32_bf16 v[52:55], v[184:187], v[204:207], v[52:55]
	v_mfma_f32_16x16x32_bf16 v[48:51], v[192:195], v[204:207], v[48:51]
	v_mfma_f32_16x16x32_bf16 v[36:39], v[184:187], v[212:215], v[36:39]
	v_mfma_f32_16x16x32_bf16 v[32:35], v[192:195], v[212:215], v[32:35]
	v_mfma_f32_16x16x32_bf16 v[20:23], v[184:187], v[220:223], v[20:23]
	v_mfma_f32_16x16x32_bf16 v[16:19], v[192:195], v[220:223], v[16:19]
	v_mfma_f32_16x16x32_bf16 v[4:7], v[184:187], v[228:231], v[4:7]
	v_mfma_f32_16x16x32_bf16 v[0:3], v[192:195], v[228:231], v[0:3]
	v_mfma_f32_16x16x32_bf16 v[52:55], v[188:191], v[208:211], v[52:55]
	v_mfma_f32_16x16x32_bf16 v[48:51], v[196:199], v[208:211], v[48:51]
	v_mfma_f32_16x16x32_bf16 v[36:39], v[188:191], v[216:219], v[36:39]
	v_mfma_f32_16x16x32_bf16 v[32:35], v[196:199], v[216:219], v[32:35]
	v_mfma_f32_16x16x32_bf16 v[20:23], v[188:191], v[224:227], v[20:23]
	v_mfma_f32_16x16x32_bf16 v[16:19], v[196:199], v[224:227], v[16:19]
	v_mfma_f32_16x16x32_bf16 v[4:7], v[188:191], v[244:247], v[4:7]
	v_mfma_f32_16x16x32_bf16 v[0:3], v[196:199], v[244:247], v[0:3]
	s_setprio 0
	s_barrier
	s_add_i32 s25, s25, 2
	s_add_u32 s23, s23, 0x100
	s_addc_u32 s24, s24, 0
	s_add_u32 s0, s0, 0x100
	s_addc_u32 s1, s1, 0
	s_cmp_gt_u32 s25, 29
	s_cbranch_scc0 .LBB0_346
	s_and_b64 vcc, exec, s[6:7]
	s_cbranch_vccz .LBB0_349
	s_barrier

; #define PG8_STAGE(bufoff, gbase, voff) do { _Pragma("unroll") for (int _i = 0; _i < 2; ++_i) \
;         __builtin_amdgcn_global_load_lds((const unsigned*)((const char*)(gbase) + (voff)[_i]), (LAS unsigned*)(lds + (bufoff) + ldsw + _i * 8192), 16, 0, 0); } while (0)
; #define PG8_LDA(dst, b, h) do { _Pragma("unroll") for (int m = 0; m < 4; ++m) _Pragma("unroll") for (int k = 0; k < 2; ++k) dst[m][k] = *(const LAS bf16x8*)(lds + PG8_SA(b, h) + aoff + m * 2048 + k * 1024); } while (0)
; #define PG8_LDB(dst, b, h) do { _Pragma("unroll") for (int n = 0; n < 2; ++n) _Pragma("unroll") for (int k = 0; k < 2; ++k) dst[n][k] = *(const LAS bf16x8*)(lds + PG8_SB(b, h) + boff + n * 2048 + k * 1024); } while (0)
; #define PG8_MMA(ai, bj, At, Bt) do { __builtin_amdgcn_s_setprio(1); _Pragma("unroll") for (int m = 0; m < 4; ++m) _Pragma("unroll") for (int n = 0; n < 2; ++n) _Pragma("unroll") for (int k = 0; k < 2; ++k) \
;         acc[ai][bj][m][n] = __builtin_amdgcn_mfma_f32_16x16x32_bf16(Bt[n][k], At[m][k], acc[ai][bj][m][n], 0, 0, 0); __builtin_amdgcn_s_setprio(0); } while (0)
; #define PG8_WAIT_V(n) asm volatile("s_waitcnt vmcnt(" #n ")" ::: "memory")
; #define PG8_WAIT_L(n) asm volatile("s_waitcnt lgkmcnt(" #n ")" ::: "memory")
; template <class Epi, class Sched, bool APERM = false, bool HALFN = false>
; __device__ __forceinline__ void gemm_phase(LAS unsigned char* lds, const int tid_in, const int K, const Sched& S, const Epi& E) {
;     ...
;         for (int t = 0; t < nt; t += 2) {
;             const bool last = (t == nt - 2);
;             const char* a1 = cA + (size_t)(t + 1) * kstep;
;             const char* a2 = last ? nA : cA + (size_t)(t + 2) * kstep; const char* b2 = last ? nB : cB + (size_t)(t + 2) * kstep;
;             const char* a3 = a2 + kstep; const char* b3 = b2 + kstep;
;             PG8_LDB(B0, 0, 0); PG8_LDB(B1, 0, 1); PG8_SCHED; PG8_LDA(At, 0, 0); PG8_STAGE(PG8_SA(1, 1), a1 + hstepA, voffA);
;             PG8_WAIT_V(8); PG8_WAIT_L(0); PG8_BAR; PG8_MMA(0, 0, At, B0); if constexpr (!HALFN) PG8_MMA(0, 1, At, B1); PG8_BAR; PG8_SCHED;
;             PG8_LDA(At, 0, 1); PG8_STAGE(PG8_SB(0, 0), b2, voffB); PG8_STAGE(PG8_SB(0, 1), b2 + hstep, voffB); PG8_STAGE(PG8_SA(0, 0), a2, voffA);
;             PG8_WAIT_V(8); PG8_WAIT_L(0); PG8_BAR; PG8_MMA(1, 0, At, B0); if constexpr (!HALFN) PG8_MMA(1, 1, At, B1); PG8_BAR; PG8_SCHED;
.LBB0_682:
	s_add_u32 s18, s16, 0xfff80080
	s_addc_u32 s19, s17, -1
	s_add_i32 s57, 0, 0x10000
	s_cmp_eq_u32 s53, 28
	s_cselect_b32 s21, s11, s19
	s_cselect_b32 s20, s10, s18
	s_cselect_b32 s19, s13, s52
	s_cselect_b32 s18, s12, s45
	s_add_i32 s72, 0, 0x14000
	v_add_u32_e32 v128, s57, v220
	v_add_u32_e32 v156, s72, v220
	ds_read_b128 v[112:115], v128
	ds_read_b128 v[116:119], v128 offset:1024
	ds_read_b128 v[120:123], v128 offset:2048
	ds_read_b128 v[128:131], v128 offset:3072
	ds_read_b128 v[136:139], v156
	ds_read_b128 v[140:143], v156 offset:1024
	ds_read_b128 v[144:147], v156 offset:2048
	ds_read_b128 v[156:159], v156 offset:3072
	v_lshl_add_u64 v[208:209], s[16:17], 0, v[198:199]
	s_add_i32 m0, s29, 0xc000
	ds_read_b128 v[160:163], v226
	ds_read_b128 v[164:167], v226 offset:1024
	ds_read_b128 v[168:171], v226 offset:2048
	ds_read_b128 v[172:175], v226 offset:3072
	ds_read_b128 v[176:179], v226 offset:4096
	ds_read_b128 v[180:183], v226 offset:5120
	ds_read_b128 v[184:187], v226 offset:6144
	ds_read_b128 v[204:207], v226 offset:7168
	global_load_lds_dwordx4 v[208:209], off
	v_lshl_add_u64 v[208:209], s[16:17], 0, v[196:197]
	s_add_i32 m0, s29, 0xe000
	s_nop 0
	global_load_lds_dwordx4 v[208:209], off
	s_waitcnt vmcnt(8)
	s_waitcnt lgkmcnt(0)
	s_barrier
	s_setprio 1
	s_waitcnt lgkmcnt(0)
	v_mfma_f32_16x16x32_bf16 v[152:155], v[112:115], v[160:163], v[152:155]
	v_mfma_f32_16x16x32_bf16 v[148:151], v[120:123], v[160:163], v[148:151]
	v_mfma_f32_16x16x32_bf16 v[108:111], v[112:115], v[168:171], v[108:111]
	v_mfma_f32_16x16x32_bf16 v[104:107], v[120:123], v[168:171], v[104:107]
	v_mfma_f32_16x16x32_bf16 v[92:95], v[112:115], v[176:179], v[92:95]
	v_mfma_f32_16x16x32_bf16 v[88:91], v[120:123], v[176:179], v[88:91]
	v_mfma_f32_16x16x32_bf16 v[76:79], v[112:115], v[184:187], v[76:79]
	v_mfma_f32_16x16x32_bf16 v[72:75], v[120:123], v[184:187], v[72:75]
	v_mfma_f32_16x16x32_bf16 v[152:155], v[116:119], v[164:167], v[152:155]
	v_mfma_f32_16x16x32_bf16 v[148:151], v[128:131], v[164:167], v[148:151]
	v_mfma_f32_16x16x32_bf16 v[108:111], v[116:119], v[172:175], v[108:111]
	v_mfma_f32_16x16x32_bf16 v[104:107], v[128:131], v[172:175], v[104:107]
	v_mfma_f32_16x16x32_bf16 v[92:95], v[116:119], v[180:183], v[92:95]
	v_mfma_f32_16x16x32_bf16 v[88:91], v[128:131], v[180:183], v[88:91]
	v_mfma_f32_16x16x32_bf16 v[76:79], v[116:119], v[204:207], v[76:79]
	v_mfma_f32_16x16x32_bf16 v[72:75], v[128:131], v[204:207], v[72:75]
	v_mfma_f32_16x16x32_bf16 v[132:135], v[136:139], v[160:163], v[132:135]
	v_mfma_f32_16x16x32_bf16 v[124:127], v[144:147], v[160:163], v[124:127]
	v_mfma_f32_16x16x32_bf16 v[100:103], v[136:139], v[168:171], v[100:103]
	v_mfma_f32_16x16x32_bf16 v[96:99], v[144:147], v[168:171], v[96:99]
	v_mfma_f32_16x16x32_bf16 v[84:87], v[136:139], v[176:179], v[84:87]
	v_mfma_f32_16x16x32_bf16 v[80:83], v[144:147], v[176:179], v[80:83]
	v_mfma_f32_16x16x32_bf16 v[68:71], v[136:139], v[184:187], v[68:71]
	v_mfma_f32_16x16x32_bf16 v[64:67], v[144:147], v[184:187], v[64:67]
	v_mfma_f32_16x16x32_bf16 v[132:135], v[140:143], v[164:167], v[132:135]
	v_mfma_f32_16x16x32_bf16 v[124:127], v[156:159], v[164:167], v[124:127]
	v_mfma_f32_16x16x32_bf16 v[100:103], v[140:143], v[172:175], v[100:103]
	v_mfma_f32_16x16x32_bf16 v[96:99], v[156:159], v[172:175], v[96:99]
	v_mfma_f32_16x16x32_bf16 v[84:87], v[140:143], v[180:183], v[84:87]
	v_mfma_f32_16x16x32_bf16 v[80:83], v[156:159], v[180:183], v[80:83]
	v_mfma_f32_16x16x32_bf16 v[68:71], v[140:143], v[204:207], v[68:71]
	v_mfma_f32_16x16x32_bf16 v[64:67], v[156:159], v[204:207], v[64:67]
	s_setprio 0
	s_barrier
	s_add_i32 s57, s57, s28
	v_lshl_add_u64 v[208:209], s[18:19], 0, v[200:201]
	s_mov_b32 m0, s57
	ds_read_b128 v[160:163], v226 offset:16384
	ds_read_b128 v[164:167], v226 offset:17408
	ds_read_b128 v[168:171], v226 offset:18432
	ds_read_b128 v[172:175], v226 offset:19456
	ds_read_b128 v[176:179], v226 offset:20480
	ds_read_b128 v[180:183], v226 offset:21504
	ds_read_b128 v[184:187], v226 offset:22528
	ds_read_b128 v[204:207], v226 offset:23552
	global_load_lds_dwordx4 v[208:209], off
	s_add_i32 m0, s57, 0x2000
	s_add_u32 s70, s18, 0x80000
	v_lshl_add_u64 v[210:211], s[18:19], 0, v[192:193]
	s_addc_u32 s71, s19, 0
	s_add_i32 s57, s72, s28
	global_load_lds_dwordx4 v[210:211], off
	v_lshl_add_u64 v[212:213], s[70:71], 0, v[200:201]
	s_mov_b32 m0, s57
	v_lshl_add_u64 v[214:215], s[20:21], 0, v[190:191]
	global_load_lds_dwordx4 v[212:213], off
	v_lshl_add_u64 v[212:213], s[70:71], 0, v[192:193]
	s_add_i32 m0, s57, 0x2000
	s_nop 0
	global_load_lds_dwordx4 v[212:213], off
	v_lshl_add_u64 v[212:213], s[20:21], 0, v[188:189]
	s_mov_b32 m0, s29
	s_nop 0
	global_load_lds_dwordx4 v[212:213], off
	s_mov_b32 m0, s30
	s_nop 0
	global_load_lds_dwordx4 v[214:215], off
	s_waitcnt vmcnt(8)
	s_waitcnt lgkmcnt(0)
	s_barrier
; #define PG8_STAGE(bufoff, gbase, voff) do { _Pragma("unroll") for (int _i = 0; _i < 2; ++_i) \
;         __builtin_amdgcn_global_load_lds((const unsigned*)((const char*)(gbase) + (voff)[_i]), (LAS unsigned*)(lds + (bufoff) + ldsw + _i * 8192), 16, 0, 0); } while (0)
; #define PG8_LDA(dst, b, h) do { _Pragma("unroll") for (int m = 0; m < 4; ++m) _Pragma("unroll") for (int k = 0; k < 2; ++k) dst[m][k] = *(const LAS bf16x8*)(lds + PG8_SA(b, h) + aoff + m * 2048 + k * 1024); } while (0)
; #define PG8_LDB(dst, b, h) do { _Pragma("unroll") for (int n = 0; n < 2; ++n) _Pragma("unroll") for (int k = 0; k < 2; ++k) dst[n][k] = *(const LAS bf16x8*)(lds + PG8_SB(b, h) + boff + n * 2048 + k * 1024); } while (0)
; #define PG8_MMA(ai, bj, At, Bt) do { __builtin_amdgcn_s_setprio(1); _Pragma("unroll") for (int m = 0; m < 4; ++m) _Pragma("unroll") for (int n = 0; n < 2; ++n) _Pragma("unroll") for (int k = 0; k < 2; ++k) \
;         acc[ai][bj][m][n] = __builtin_amdgcn_mfma_f32_16x16x32_bf16(Bt[n][k], At[m][k], acc[ai][bj][m][n], 0, 0, 0); __builtin_amdgcn_s_setprio(0); } while (0)
; #define PG8_WAIT_V(n) asm volatile("s_waitcnt vmcnt(" #n ")" ::: "memory")
; #define PG8_WAIT_L(n) asm volatile("s_waitcnt lgkmcnt(" #n ")" ::: "memory")
; #define PG8_BAR __builtin_amdgcn_s_barrier()
; #define PG8_SCHED __builtin_amdgcn_sched_barrier(0)
; template <class Epi, class Sched, bool APERM = false, bool HALFN = false>
; __device__ __forceinline__ void gemm_phase(LAS unsigned char* lds, const int tid_in, const int K, const Sched& S, const Epi& E) {
;     ...
;             PG8_WAIT_V(8); PG8_WAIT_L(0); PG8_BAR; PG8_MMA(1, 0, At, B0); if constexpr (!HALFN) PG8_MMA(1, 1, At, B1); PG8_BAR; PG8_SCHED;
;             PG8_LDB(B0, 1, 0); PG8_LDB(B1, 1, 1); PG8_SCHED; PG8_LDA(At, 1, 0); PG8_STAGE(PG8_SA(0, 1), a2 + hstepA, voffA);
;             PG8_WAIT_V(8); PG8_WAIT_L(0); PG8_BAR; PG8_MMA(0, 0, At, B0); if constexpr (!HALFN) PG8_MMA(0, 1, At, B1); PG8_BAR; PG8_SCHED;
;             PG8_LDA(At, 1, 1); PG8_STAGE(PG8_SB(1, 0), b3, voffB); PG8_STAGE(PG8_SB(1, 1), b3 + hstep, voffB); PG8_STAGE(PG8_SA(1, 0), a3, voffA);
	s_setprio 1
	s_waitcnt lgkmcnt(0)
	v_mfma_f32_16x16x32_bf16 v[60:63], v[112:115], v[160:163], v[60:63]
	v_mfma_f32_16x16x32_bf16 v[56:59], v[120:123], v[160:163], v[56:59]
	v_mfma_f32_16x16x32_bf16 v[44:47], v[112:115], v[168:171], v[44:47]
	v_mfma_f32_16x16x32_bf16 v[40:43], v[120:123], v[168:171], v[40:43]
	v_mfma_f32_16x16x32_bf16 v[28:31], v[112:115], v[176:179], v[28:31]
	v_mfma_f32_16x16x32_bf16 v[24:27], v[120:123], v[176:179], v[24:27]
	v_mfma_f32_16x16x32_bf16 v[12:15], v[112:115], v[184:187], v[12:15]
	v_mfma_f32_16x16x32_bf16 v[8:11], v[120:123], v[184:187], v[8:11]
	v_mfma_f32_16x16x32_bf16 v[60:63], v[116:119], v[164:167], v[60:63]
	v_mfma_f32_16x16x32_bf16 v[56:59], v[128:131], v[164:167], v[56:59]
	v_mfma_f32_16x16x32_bf16 v[44:47], v[116:119], v[172:175], v[44:47]
	v_mfma_f32_16x16x32_bf16 v[40:43], v[128:131], v[172:175], v[40:43]
	v_mfma_f32_16x16x32_bf16 v[28:31], v[116:119], v[180:183], v[28:31]
	v_mfma_f32_16x16x32_bf16 v[24:27], v[128:131], v[180:183], v[24:27]
	v_mfma_f32_16x16x32_bf16 v[12:15], v[116:119], v[204:207], v[12:15]
	v_mfma_f32_16x16x32_bf16 v[8:11], v[128:131], v[204:207], v[8:11]
	v_mfma_f32_16x16x32_bf16 v[52:55], v[136:139], v[160:163], v[52:55]
	v_mfma_f32_16x16x32_bf16 v[48:51], v[144:147], v[160:163], v[48:51]
	v_mfma_f32_16x16x32_bf16 v[36:39], v[136:139], v[168:171], v[36:39]
	v_mfma_f32_16x16x32_bf16 v[32:35], v[144:147], v[168:171], v[32:35]
	v_mfma_f32_16x16x32_bf16 v[20:23], v[136:139], v[176:179], v[20:23]
	v_mfma_f32_16x16x32_bf16 v[16:19], v[144:147], v[176:179], v[16:19]
	v_mfma_f32_16x16x32_bf16 v[4:7], v[136:139], v[184:187], v[4:7]
	v_mfma_f32_16x16x32_bf16 v[0:3], v[144:147], v[184:187], v[0:3]
	v_mfma_f32_16x16x32_bf16 v[52:55], v[140:143], v[164:167], v[52:55]
	v_mfma_f32_16x16x32_bf16 v[48:51], v[156:159], v[164:167], v[48:51]
	v_mfma_f32_16x16x32_bf16 v[36:39], v[140:143], v[172:175], v[36:39]
	v_mfma_f32_16x16x32_bf16 v[32:35], v[156:159], v[172:175], v[32:35]
	v_mfma_f32_16x16x32_bf16 v[20:23], v[140:143], v[180:183], v[20:23]
	v_mfma_f32_16x16x32_bf16 v[16:19], v[156:159], v[180:183], v[16:19]
	v_mfma_f32_16x16x32_bf16 v[4:7], v[140:143], v[204:207], v[4:7]
	v_mfma_f32_16x16x32_bf16 v[0:3], v[156:159], v[204:207], v[0:3]
	s_setprio 0
	s_barrier
	s_add_i32 s57, 0, 0x18000
	s_add_i32 s70, 0, 0x1c000
	v_add_u32_e32 v128, s57, v220
	v_add_u32_e32 v156, s70, v220
	ds_read_b128 v[112:115], v128
	ds_read_b128 v[116:119], v128 offset:1024
	ds_read_b128 v[120:123], v128 offset:2048
	ds_read_b128 v[128:131], v128 offset:3072
	ds_read_b128 v[136:139], v156
	ds_read_b128 v[140:143], v156 offset:1024
	ds_read_b128 v[144:147], v156 offset:2048
	ds_read_b128 v[156:159], v156 offset:3072
	s_add_u32 s20, s20, 0x80000
	s_addc_u32 s21, s21, 0
	s_mov_b32 m0, s31
	v_lshl_add_u64 v[216:217], s[20:21], 0, v[188:189]
	ds_read_b128 v[160:163], v226 offset:32768
	ds_read_b128 v[164:167], v226 offset:33792
	ds_read_b128 v[168:171], v226 offset:34816
	ds_read_b128 v[172:175], v226 offset:35840
	ds_read_b128 v[176:179], v226 offset:36864
	ds_read_b128 v[180:183], v226 offset:37888
	ds_read_b128 v[184:187], v226 offset:38912
	ds_read_b128 v[204:207], v226 offset:39936
	global_load_lds_dwordx4 v[216:217], off
	v_lshl_add_u64 v[216:217], s[20:21], 0, v[190:191]
	s_mov_b32 m0, s34
	s_nop 0
	global_load_lds_dwordx4 v[216:217], off
	s_waitcnt vmcnt(8)
	s_waitcnt lgkmcnt(0)
	s_barrier
	s_setprio 1
	s_waitcnt lgkmcnt(0)
	v_mfma_f32_16x16x32_bf16 v[152:155], v[112:115], v[160:163], v[152:155]
	v_mfma_f32_16x16x32_bf16 v[148:151], v[120:123], v[160:163], v[148:151]
	v_mfma_f32_16x16x32_bf16 v[108:111], v[112:115], v[168:171], v[108:111]
	v_mfma_f32_16x16x32_bf16 v[104:107], v[120:123], v[168:171], v[104:107]
	v_mfma_f32_16x16x32_bf16 v[92:95], v[112:115], v[176:179], v[92:95]
	v_mfma_f32_16x16x32_bf16 v[88:91], v[120:123], v[176:179], v[88:91]
	v_mfma_f32_16x16x32_bf16 v[76:79], v[112:115], v[184:187], v[76:79]
	v_mfma_f32_16x16x32_bf16 v[72:75], v[120:123], v[184:187], v[72:75]
	v_mfma_f32_16x16x32_bf16 v[152:155], v[116:119], v[164:167], v[152:155]
	v_mfma_f32_16x16x32_bf16 v[148:151], v[128:131], v[164:167], v[148:151]
	v_mfma_f32_16x16x32_bf16 v[108:111], v[116:119], v[172:175], v[108:111]
	v_mfma_f32_16x16x32_bf16 v[104:107], v[128:131], v[172:175], v[104:107]
	v_mfma_f32_16x16x32_bf16 v[92:95], v[116:119], v[180:183], v[92:95]
	v_mfma_f32_16x16x32_bf16 v[88:91], v[128:131], v[180:183], v[88:91]
	v_mfma_f32_16x16x32_bf16 v[76:79], v[116:119], v[204:207], v[76:79]
	v_mfma_f32_16x16x32_bf16 v[72:75], v[128:131], v[204:207], v[72:75]
	v_mfma_f32_16x16x32_bf16 v[132:135], v[136:139], v[160:163], v[132:135]
	v_mfma_f32_16x16x32_bf16 v[124:127], v[144:147], v[160:163], v[124:127]
	v_mfma_f32_16x16x32_bf16 v[100:103], v[136:139], v[168:171], v[100:103]
	v_mfma_f32_16x16x32_bf16 v[96:99], v[144:147], v[168:171], v[96:99]
	v_mfma_f32_16x16x32_bf16 v[84:87], v[136:139], v[176:179], v[84:87]
	v_mfma_f32_16x16x32_bf16 v[80:83], v[144:147], v[176:179], v[80:83]
	v_mfma_f32_16x16x32_bf16 v[68:71], v[136:139], v[184:187], v[68:71]
	v_mfma_f32_16x16x32_bf16 v[64:67], v[144:147], v[184:187], v[64:67]
	v_mfma_f32_16x16x32_bf16 v[132:135], v[140:143], v[164:167], v[132:135]
	v_mfma_f32_16x16x32_bf16 v[124:127], v[156:159], v[164:167], v[124:127]
	v_mfma_f32_16x16x32_bf16 v[100:103], v[140:143], v[172:175], v[100:103]
	v_mfma_f32_16x16x32_bf16 v[96:99], v[156:159], v[172:175], v[96:99]
	v_mfma_f32_16x16x32_bf16 v[84:87], v[140:143], v[180:183], v[84:87]
	v_mfma_f32_16x16x32_bf16 v[80:83], v[156:159], v[180:183], v[80:83]
	v_mfma_f32_16x16x32_bf16 v[68:71], v[140:143], v[204:207], v[68:71]
	v_mfma_f32_16x16x32_bf16 v[64:67], v[156:159], v[204:207], v[64:67]
	s_setprio 0
	s_barrier
; #define PG8_STAGE(bufoff, gbase, voff) do { _Pragma("unroll") for (int _i = 0; _i < 2; ++_i) \
;         __builtin_amdgcn_global_load_lds((const unsigned*)((const char*)(gbase) + (voff)[_i]), (LAS unsigned*)(lds + (bufoff) + ldsw + _i * 8192), 16, 0, 0); } while (0)
; #define PG8_LDA(dst, b, h) do { _Pragma("unroll") for (int m = 0; m < 4; ++m) _Pragma("unroll") for (int k = 0; k < 2; ++k) dst[m][k] = *(const LAS bf16x8*)(lds + PG8_SA(b, h) + aoff + m * 2048 + k * 1024); } while (0)
; #define PG8_MMA(ai, bj, At, Bt) do { __builtin_amdgcn_s_setprio(1); _Pragma("unroll") for (int m = 0; m < 4; ++m) _Pragma("unroll") for (int n = 0; n < 2; ++n) _Pragma("unroll") for (int k = 0; k < 2; ++k) \
;         acc[ai][bj][m][n] = __builtin_amdgcn_mfma_f32_16x16x32_bf16(Bt[n][k], At[m][k], acc[ai][bj][m][n], 0, 0, 0); __builtin_amdgcn_s_setprio(0); } while (0)
; #define PG8_WAIT_V(n) asm volatile("s_waitcnt vmcnt(" #n ")" ::: "memory")
; #define PG8_WAIT_L(n) asm volatile("s_waitcnt lgkmcnt(" #n ")" ::: "memory")
; #define PG8_BAR __builtin_amdgcn_s_barrier()
; #define PG8_SCHED __builtin_amdgcn_sched_barrier(0)
; template <class Epi, class Sched, bool APERM = false, bool HALFN = false>
; __device__ __forceinline__ void gemm_phase(LAS unsigned char* lds, const int tid_in, const int K, const Sched& S, const Epi& E) {
;     ...
;             PG8_LDA(At, 1, 1); PG8_STAGE(PG8_SB(1, 0), b3, voffB); PG8_STAGE(PG8_SB(1, 1), b3 + hstep, voffB); PG8_STAGE(PG8_SA(1, 0), a3, voffA);
;             PG8_WAIT_V(8); PG8_WAIT_L(0); PG8_BAR; PG8_MMA(1, 0, At, B0); if constexpr (!HALFN) PG8_MMA(1, 1, At, B1); PG8_BAR; PG8_SCHED;
;         }
	s_add_i32 s20, s57, s28
	v_lshl_add_u64 v[208:209], v[208:209], 0, s[78:79]
	s_mov_b32 m0, s20
	ds_read_b128 v[160:163], v226 offset:49152
	ds_read_b128 v[164:167], v226 offset:50176
	ds_read_b128 v[168:171], v226 offset:51200
	ds_read_b128 v[172:175], v226 offset:52224
	ds_read_b128 v[176:179], v226 offset:53248
	ds_read_b128 v[180:183], v226 offset:54272
	ds_read_b128 v[184:187], v226 offset:55296
	ds_read_b128 v[204:207], v226 offset:56320
	global_load_lds_dwordx4 v[208:209], off
	s_add_i32 m0, s20, 0x2000
	s_add_u32 s18, s18, 0x80080
	v_lshl_add_u64 v[208:209], v[210:211], 0, s[78:79]
	s_addc_u32 s19, s19, 0
	s_add_i32 s20, s70, s28
	global_load_lds_dwordx4 v[208:209], off
	v_lshl_add_u64 v[208:209], s[18:19], 0, v[200:201]
	s_mov_b32 m0, s20
	s_nop 0
	global_load_lds_dwordx4 v[208:209], off
	v_lshl_add_u64 v[208:209], s[18:19], 0, v[192:193]
	s_add_i32 m0, s20, 0x2000
	s_nop 0
	global_load_lds_dwordx4 v[208:209], off
	v_lshl_add_u64 v[208:209], v[212:213], 0, s[78:79]
	s_mov_b32 m0, s35
	s_nop 0
	global_load_lds_dwordx4 v[208:209], off
	v_lshl_add_u64 v[208:209], v[214:215], 0, s[78:79]
	s_mov_b32 m0, s38
	s_nop 0
	global_load_lds_dwordx4 v[208:209], off
	s_waitcnt vmcnt(8)
	s_waitcnt lgkmcnt(0)
	s_barrier
	s_setprio 1
	s_waitcnt lgkmcnt(0)
	v_mfma_f32_16x16x32_bf16 v[60:63], v[112:115], v[160:163], v[60:63]
	v_mfma_f32_16x16x32_bf16 v[56:59], v[120:123], v[160:163], v[56:59]
	v_mfma_f32_16x16x32_bf16 v[44:47], v[112:115], v[168:171], v[44:47]
	v_mfma_f32_16x16x32_bf16 v[40:43], v[120:123], v[168:171], v[40:43]
	v_mfma_f32_16x16x32_bf16 v[28:31], v[112:115], v[176:179], v[28:31]
	v_mfma_f32_16x16x32_bf16 v[24:27], v[120:123], v[176:179], v[24:27]
	v_mfma_f32_16x16x32_bf16 v[12:15], v[112:115], v[184:187], v[12:15]
	v_mfma_f32_16x16x32_bf16 v[8:11], v[120:123], v[184:187], v[8:11]
	v_mfma_f32_16x16x32_bf16 v[60:63], v[116:119], v[164:167], v[60:63]
	v_mfma_f32_16x16x32_bf16 v[56:59], v[128:131], v[164:167], v[56:59]
	v_mfma_f32_16x16x32_bf16 v[44:47], v[116:119], v[172:175], v[44:47]
	v_mfma_f32_16x16x32_bf16 v[40:43], v[128:131], v[172:175], v[40:43]
	v_mfma_f32_16x16x32_bf16 v[28:31], v[116:119], v[180:183], v[28:31]
	v_mfma_f32_16x16x32_bf16 v[24:27], v[128:131], v[180:183], v[24:27]
	v_mfma_f32_16x16x32_bf16 v[12:15], v[116:119], v[204:207], v[12:15]
	v_mfma_f32_16x16x32_bf16 v[8:11], v[128:131], v[204:207], v[8:11]
	v_mfma_f32_16x16x32_bf16 v[52:55], v[136:139], v[160:163], v[52:55]
	v_mfma_f32_16x16x32_bf16 v[48:51], v[144:147], v[160:163], v[48:51]
	v_mfma_f32_16x16x32_bf16 v[36:39], v[136:139], v[168:171], v[36:39]
	v_mfma_f32_16x16x32_bf16 v[32:35], v[144:147], v[168:171], v[32:35]
	v_mfma_f32_16x16x32_bf16 v[20:23], v[136:139], v[176:179], v[20:23]
	v_mfma_f32_16x16x32_bf16 v[16:19], v[144:147], v[176:179], v[16:19]
	v_mfma_f32_16x16x32_bf16 v[4:7], v[136:139], v[184:187], v[4:7]
	v_mfma_f32_16x16x32_bf16 v[0:3], v[144:147], v[184:187], v[0:3]
	v_mfma_f32_16x16x32_bf16 v[52:55], v[140:143], v[164:167], v[52:55]
	v_mfma_f32_16x16x32_bf16 v[48:51], v[156:159], v[164:167], v[48:51]
	v_mfma_f32_16x16x32_bf16 v[36:39], v[140:143], v[172:175], v[36:39]
	v_mfma_f32_16x16x32_bf16 v[32:35], v[156:159], v[172:175], v[32:35]
	v_mfma_f32_16x16x32_bf16 v[20:23], v[140:143], v[180:183], v[20:23]
	v_mfma_f32_16x16x32_bf16 v[16:19], v[156:159], v[180:183], v[16:19]
	v_mfma_f32_16x16x32_bf16 v[4:7], v[140:143], v[204:207], v[4:7]
	v_mfma_f32_16x16x32_bf16 v[0:3], v[156:159], v[204:207], v[0:3]
	s_setprio 0
	s_barrier
	s_add_i32 s53, s53, 2
	s_add_u32 s45, s45, 0x100
	s_addc_u32 s52, s52, 0
	s_add_u32 s16, s16, 0x100
	s_addc_u32 s17, s17, 0
	s_cmp_gt_u32 s53, 29
	s_cbranch_scc0 .LBB0_682
	s_and_b64 vcc, exec, s[8:9]
	s_cbranch_vccz .LBB0_685
	s_barrier

; #define PG8_STAGE(bufoff, gbase, voff) do { _Pragma("unroll") for (int _i = 0; _i < 2; ++_i) \
;         __builtin_amdgcn_global_load_lds((const unsigned*)((const char*)(gbase) + (voff)[_i]), (LAS unsigned*)(lds + (bufoff) + ldsw + _i * 8192), 16, 0, 0); } while (0)
; #define PG8_LDA(dst, b, h) do { _Pragma("unroll") for (int m = 0; m < 4; ++m) _Pragma("unroll") for (int k = 0; k < 2; ++k) dst[m][k] = *(const LAS bf16x8*)(lds + PG8_SA(b, h) + aoff + m * 2048 + k * 1024); } while (0)
; #define PG8_LDB(dst, b, h) do { _Pragma("unroll") for (int n = 0; n < 2; ++n) _Pragma("unroll") for (int k = 0; k < 2; ++k) dst[n][k] = *(const LAS bf16x8*)(lds + PG8_SB(b, h) + boff + n * 2048 + k * 1024); } while (0)
; #define PG8_MMA(ai, bj, At, Bt) do { __builtin_amdgcn_s_setprio(1); _Pragma("unroll") for (int m = 0; m < 4; ++m) _Pragma("unroll") for (int n = 0; n < 2; ++n) _Pragma("unroll") for (int k = 0; k < 2; ++k) \
;         acc[ai][bj][m][n] = __builtin_amdgcn_mfma_f32_16x16x32_bf16(Bt[n][k], At[m][k], acc[ai][bj][m][n], 0, 0, 0); __builtin_amdgcn_s_setprio(0); } while (0)
; #define PG8_WAIT_V(n) asm volatile("s_waitcnt vmcnt(" #n ")" ::: "memory")
; #define PG8_WAIT_L(n) asm volatile("s_waitcnt lgkmcnt(" #n ")" ::: "memory")
; template <class Epi, class Sched, bool APERM = false, bool HALFN = false>
; __device__ __forceinline__ void gemm_phase(LAS unsigned char* lds, const int tid_in, const int K, const Sched& S, const Epi& E) {
;     ...
;         for (int t = 0; t < nt; t += 2) {
;             const bool last = (t == nt - 2);
;             const char* a1 = cA + (size_t)(t + 1) * kstep;
;             const char* a2 = last ? nA : cA + (size_t)(t + 2) * kstep; const char* b2 = last ? nB : cB + (size_t)(t + 2) * kstep;
;             const char* a3 = a2 + kstep; const char* b3 = b2 + kstep;
;             PG8_LDB(B0, 0, 0); PG8_LDB(B1, 0, 1); PG8_SCHED; PG8_LDA(At, 0, 0); PG8_STAGE(PG8_SA(1, 1), a1 + hstepA, voffA);
;             PG8_WAIT_V(8); PG8_WAIT_L(0); PG8_BAR; PG8_MMA(0, 0, At, B0); if constexpr (!HALFN) PG8_MMA(0, 1, At, B1); PG8_BAR; PG8_SCHED;
;             PG8_LDA(At, 0, 1); PG8_STAGE(PG8_SB(0, 0), b2, voffB); PG8_STAGE(PG8_SB(0, 1), b2 + hstep, voffB); PG8_STAGE(PG8_SA(0, 0), a2, voffA);
;             PG8_WAIT_V(8); PG8_WAIT_L(0); PG8_BAR; PG8_MMA(1, 0, At, B0); if constexpr (!HALFN) PG8_MMA(1, 1, At, B1); PG8_BAR; PG8_SCHED;
.LBB0_806:
	s_add_u32 s18, s16, 0xfffe0080
	s_addc_u32 s19, s17, -1
	s_add_i32 s57, 0, 0x10000
	s_cmp_eq_u32 s53, 4
	s_cselect_b32 s21, s11, s19
	s_cselect_b32 s20, s10, s18
	s_cselect_b32 s19, s13, s52
	s_cselect_b32 s18, s12, s45
	s_add_i32 s72, 0, 0x14000
	v_add_u32_e32 v128, s57, v220
	v_add_u32_e32 v156, s72, v220
	ds_read_b128 v[112:115], v128
	ds_read_b128 v[116:119], v128 offset:1024
	ds_read_b128 v[120:123], v128 offset:2048
	ds_read_b128 v[128:131], v128 offset:3072
	ds_read_b128 v[136:139], v156
	ds_read_b128 v[140:143], v156 offset:1024
	ds_read_b128 v[144:147], v156 offset:2048
	ds_read_b128 v[156:159], v156 offset:3072
	v_lshl_add_u64 v[208:209], s[16:17], 0, v[198:199]
	s_add_i32 m0, s29, 0xc000
	ds_read_b128 v[160:163], v226
	ds_read_b128 v[164:167], v226 offset:1024
	ds_read_b128 v[168:171], v226 offset:2048
	ds_read_b128 v[172:175], v226 offset:3072
	ds_read_b128 v[176:179], v226 offset:4096
	ds_read_b128 v[180:183], v226 offset:5120
	ds_read_b128 v[184:187], v226 offset:6144
	ds_read_b128 v[204:207], v226 offset:7168
	global_load_lds_dwordx4 v[208:209], off
	v_lshl_add_u64 v[208:209], s[16:17], 0, v[196:197]
	s_add_i32 m0, s29, 0xe000
	s_nop 0
	global_load_lds_dwordx4 v[208:209], off
	s_waitcnt vmcnt(8)
	s_waitcnt lgkmcnt(0)
	s_barrier
	s_setprio 1
	s_waitcnt lgkmcnt(0)
	v_mfma_f32_16x16x32_bf16 v[152:155], v[112:115], v[160:163], v[152:155]
	v_mfma_f32_16x16x32_bf16 v[148:151], v[120:123], v[160:163], v[148:151]
	v_mfma_f32_16x16x32_bf16 v[108:111], v[112:115], v[168:171], v[108:111]
	v_mfma_f32_16x16x32_bf16 v[104:107], v[120:123], v[168:171], v[104:107]
	v_mfma_f32_16x16x32_bf16 v[92:95], v[112:115], v[176:179], v[92:95]
	v_mfma_f32_16x16x32_bf16 v[88:91], v[120:123], v[176:179], v[88:91]
	v_mfma_f32_16x16x32_bf16 v[76:79], v[112:115], v[184:187], v[76:79]
	v_mfma_f32_16x16x32_bf16 v[72:75], v[120:123], v[184:187], v[72:75]
	v_mfma_f32_16x16x32_bf16 v[152:155], v[116:119], v[164:167], v[152:155]
	v_mfma_f32_16x16x32_bf16 v[148:151], v[128:131], v[164:167], v[148:151]
	v_mfma_f32_16x16x32_bf16 v[108:111], v[116:119], v[172:175], v[108:111]
	v_mfma_f32_16x16x32_bf16 v[104:107], v[128:131], v[172:175], v[104:107]
	v_mfma_f32_16x16x32_bf16 v[92:95], v[116:119], v[180:183], v[92:95]
	v_mfma_f32_16x16x32_bf16 v[88:91], v[128:131], v[180:183], v[88:91]
	v_mfma_f32_16x16x32_bf16 v[76:79], v[116:119], v[204:207], v[76:79]
	v_mfma_f32_16x16x32_bf16 v[72:75], v[128:131], v[204:207], v[72:75]
	v_mfma_f32_16x16x32_bf16 v[132:135], v[136:139], v[160:163], v[132:135]
	v_mfma_f32_16x16x32_bf16 v[124:127], v[144:147], v[160:163], v[124:127]
	v_mfma_f32_16x16x32_bf16 v[100:103], v[136:139], v[168:171], v[100:103]
	v_mfma_f32_16x16x32_bf16 v[96:99], v[144:147], v[168:171], v[96:99]
	v_mfma_f32_16x16x32_bf16 v[84:87], v[136:139], v[176:179], v[84:87]
	v_mfma_f32_16x16x32_bf16 v[80:83], v[144:147], v[176:179], v[80:83]
	v_mfma_f32_16x16x32_bf16 v[68:71], v[136:139], v[184:187], v[68:71]
	v_mfma_f32_16x16x32_bf16 v[64:67], v[144:147], v[184:187], v[64:67]
	v_mfma_f32_16x16x32_bf16 v[132:135], v[140:143], v[164:167], v[132:135]
	v_mfma_f32_16x16x32_bf16 v[124:127], v[156:159], v[164:167], v[124:127]
	v_mfma_f32_16x16x32_bf16 v[100:103], v[140:143], v[172:175], v[100:103]
	v_mfma_f32_16x16x32_bf16 v[96:99], v[156:159], v[172:175], v[96:99]
	v_mfma_f32_16x16x32_bf16 v[84:87], v[140:143], v[180:183], v[84:87]
	v_mfma_f32_16x16x32_bf16 v[80:83], v[156:159], v[180:183], v[80:83]
	v_mfma_f32_16x16x32_bf16 v[68:71], v[140:143], v[204:207], v[68:71]
	v_mfma_f32_16x16x32_bf16 v[64:67], v[156:159], v[204:207], v[64:67]
	s_setprio 0
	s_barrier
	s_add_i32 s57, s57, s28
	v_lshl_add_u64 v[208:209], s[18:19], 0, v[200:201]
	s_mov_b32 m0, s57
	ds_read_b128 v[160:163], v226 offset:16384
	ds_read_b128 v[164:167], v226 offset:17408
	ds_read_b128 v[168:171], v226 offset:18432
	ds_read_b128 v[172:175], v226 offset:19456
	ds_read_b128 v[176:179], v226 offset:20480
	ds_read_b128 v[180:183], v226 offset:21504
	ds_read_b128 v[184:187], v226 offset:22528
	ds_read_b128 v[204:207], v226 offset:23552
	global_load_lds_dwordx4 v[208:209], off
	s_add_i32 m0, s57, 0x2000
	s_add_u32 s70, s18, 0x20000
	v_lshl_add_u64 v[210:211], s[18:19], 0, v[192:193]
	s_addc_u32 s71, s19, 0
	s_add_i32 s57, s72, s28
	global_load_lds_dwordx4 v[210:211], off
	v_lshl_add_u64 v[212:213], s[70:71], 0, v[200:201]
	s_mov_b32 m0, s57
	v_lshl_add_u64 v[214:215], s[20:21], 0, v[190:191]
	global_load_lds_dwordx4 v[212:213], off
	v_lshl_add_u64 v[212:213], s[70:71], 0, v[192:193]
	s_add_i32 m0, s57, 0x2000
	s_nop 0
	global_load_lds_dwordx4 v[212:213], off
	v_lshl_add_u64 v[212:213], s[20:21], 0, v[188:189]
	s_mov_b32 m0, s29
	s_nop 0
	global_load_lds_dwordx4 v[212:213], off
	s_mov_b32 m0, s30
	s_nop 0
	global_load_lds_dwordx4 v[214:215], off
	s_waitcnt vmcnt(8)
	s_waitcnt lgkmcnt(0)
	s_barrier
; #define PG8_STAGE(bufoff, gbase, voff) do { _Pragma("unroll") for (int _i = 0; _i < 2; ++_i) \
;         __builtin_amdgcn_global_load_lds((const unsigned*)((const char*)(gbase) + (voff)[_i]), (LAS unsigned*)(lds + (bufoff) + ldsw + _i * 8192), 16, 0, 0); } while (0)
; #define PG8_LDA(dst, b, h) do { _Pragma("unroll") for (int m = 0; m < 4; ++m) _Pragma("unroll") for (int k = 0; k < 2; ++k) dst[m][k] = *(const LAS bf16x8*)(lds + PG8_SA(b, h) + aoff + m * 2048 + k * 1024); } while (0)
; #define PG8_LDB(dst, b, h) do { _Pragma("unroll") for (int n = 0; n < 2; ++n) _Pragma("unroll") for (int k = 0; k < 2; ++k) dst[n][k] = *(const LAS bf16x8*)(lds + PG8_SB(b, h) + boff + n * 2048 + k * 1024); } while (0)
; #define PG8_MMA(ai, bj, At, Bt) do { __builtin_amdgcn_s_setprio(1); _Pragma("unroll") for (int m = 0; m < 4; ++m) _Pragma("unroll") for (int n = 0; n < 2; ++n) _Pragma("unroll") for (int k = 0; k < 2; ++k) \
;         acc[ai][bj][m][n] = __builtin_amdgcn_mfma_f32_16x16x32_bf16(Bt[n][k], At[m][k], acc[ai][bj][m][n], 0, 0, 0); __builtin_amdgcn_s_setprio(0); } while (0)
; #define PG8_WAIT_V(n) asm volatile("s_waitcnt vmcnt(" #n ")" ::: "memory")
; #define PG8_WAIT_L(n) asm volatile("s_waitcnt lgkmcnt(" #n ")" ::: "memory")
; #define PG8_BAR __builtin_amdgcn_s_barrier()
; #define PG8_SCHED __builtin_amdgcn_sched_barrier(0)
; template <class Epi, class Sched, bool APERM = false, bool HALFN = false>
; __device__ __forceinline__ void gemm_phase(LAS unsigned char* lds, const int tid_in, const int K, const Sched& S, const Epi& E) {
;     ...
;             PG8_WAIT_V(8); PG8_WAIT_L(0); PG8_BAR; PG8_MMA(1, 0, At, B0); if constexpr (!HALFN) PG8_MMA(1, 1, At, B1); PG8_BAR; PG8_SCHED;
;             PG8_LDB(B0, 1, 0); PG8_LDB(B1, 1, 1); PG8_SCHED; PG8_LDA(At, 1, 0); PG8_STAGE(PG8_SA(0, 1), a2 + hstepA, voffA);
;             PG8_WAIT_V(8); PG8_WAIT_L(0); PG8_BAR; PG8_MMA(0, 0, At, B0); if constexpr (!HALFN) PG8_MMA(0, 1, At, B1); PG8_BAR; PG8_SCHED;
;             PG8_LDA(At, 1, 1); PG8_STAGE(PG8_SB(1, 0), b3, voffB); PG8_STAGE(PG8_SB(1, 1), b3 + hstep, voffB); PG8_STAGE(PG8_SA(1, 0), a3, voffA);
	s_setprio 1
	s_waitcnt lgkmcnt(0)
	v_mfma_f32_16x16x32_bf16 v[60:63], v[112:115], v[160:163], v[60:63]
	v_mfma_f32_16x16x32_bf16 v[56:59], v[120:123], v[160:163], v[56:59]
	v_mfma_f32_16x16x32_bf16 v[44:47], v[112:115], v[168:171], v[44:47]
	v_mfma_f32_16x16x32_bf16 v[40:43], v[120:123], v[168:171], v[40:43]
	v_mfma_f32_16x16x32_bf16 v[28:31], v[112:115], v[176:179], v[28:31]
	v_mfma_f32_16x16x32_bf16 v[24:27], v[120:123], v[176:179], v[24:27]
	v_mfma_f32_16x16x32_bf16 v[12:15], v[112:115], v[184:187], v[12:15]
	v_mfma_f32_16x16x32_bf16 v[8:11], v[120:123], v[184:187], v[8:11]
	v_mfma_f32_16x16x32_bf16 v[60:63], v[116:119], v[164:167], v[60:63]
	v_mfma_f32_16x16x32_bf16 v[56:59], v[128:131], v[164:167], v[56:59]
	v_mfma_f32_16x16x32_bf16 v[44:47], v[116:119], v[172:175], v[44:47]
	v_mfma_f32_16x16x32_bf16 v[40:43], v[128:131], v[172:175], v[40:43]
	v_mfma_f32_16x16x32_bf16 v[28:31], v[116:119], v[180:183], v[28:31]
	v_mfma_f32_16x16x32_bf16 v[24:27], v[128:131], v[180:183], v[24:27]
	v_mfma_f32_16x16x32_bf16 v[12:15], v[116:119], v[204:207], v[12:15]
	v_mfma_f32_16x16x32_bf16 v[8:11], v[128:131], v[204:207], v[8:11]
	v_mfma_f32_16x16x32_bf16 v[52:55], v[136:139], v[160:163], v[52:55]
	v_mfma_f32_16x16x32_bf16 v[48:51], v[144:147], v[160:163], v[48:51]
	v_mfma_f32_16x16x32_bf16 v[36:39], v[136:139], v[168:171], v[36:39]
	v_mfma_f32_16x16x32_bf16 v[32:35], v[144:147], v[168:171], v[32:35]
	v_mfma_f32_16x16x32_bf16 v[20:23], v[136:139], v[176:179], v[20:23]
	v_mfma_f32_16x16x32_bf16 v[16:19], v[144:147], v[176:179], v[16:19]
	v_mfma_f32_16x16x32_bf16 v[4:7], v[136:139], v[184:187], v[4:7]
	v_mfma_f32_16x16x32_bf16 v[0:3], v[144:147], v[184:187], v[0:3]
	v_mfma_f32_16x16x32_bf16 v[52:55], v[140:143], v[164:167], v[52:55]
	v_mfma_f32_16x16x32_bf16 v[48:51], v[156:159], v[164:167], v[48:51]
	v_mfma_f32_16x16x32_bf16 v[36:39], v[140:143], v[172:175], v[36:39]
	v_mfma_f32_16x16x32_bf16 v[32:35], v[156:159], v[172:175], v[32:35]
	v_mfma_f32_16x16x32_bf16 v[20:23], v[140:143], v[180:183], v[20:23]
	v_mfma_f32_16x16x32_bf16 v[16:19], v[156:159], v[180:183], v[16:19]
	v_mfma_f32_16x16x32_bf16 v[4:7], v[140:143], v[204:207], v[4:7]
	v_mfma_f32_16x16x32_bf16 v[0:3], v[156:159], v[204:207], v[0:3]
	s_setprio 0
	s_barrier
	s_add_i32 s57, 0, 0x18000
	s_add_i32 s70, 0, 0x1c000
	v_add_u32_e32 v128, s57, v220
	v_add_u32_e32 v156, s70, v220
	ds_read_b128 v[112:115], v128
	ds_read_b128 v[116:119], v128 offset:1024
	ds_read_b128 v[120:123], v128 offset:2048
	ds_read_b128 v[128:131], v128 offset:3072
	ds_read_b128 v[136:139], v156
	ds_read_b128 v[140:143], v156 offset:1024
	ds_read_b128 v[144:147], v156 offset:2048
	ds_read_b128 v[156:159], v156 offset:3072
	s_add_u32 s20, s20, 0x20000
	s_addc_u32 s21, s21, 0
	s_mov_b32 m0, s31
	v_lshl_add_u64 v[216:217], s[20:21], 0, v[188:189]
	ds_read_b128 v[160:163], v226 offset:32768
	ds_read_b128 v[164:167], v226 offset:33792
	ds_read_b128 v[168:171], v226 offset:34816
	ds_read_b128 v[172:175], v226 offset:35840
	ds_read_b128 v[176:179], v226 offset:36864
	ds_read_b128 v[180:183], v226 offset:37888
	ds_read_b128 v[184:187], v226 offset:38912
	ds_read_b128 v[204:207], v226 offset:39936
	global_load_lds_dwordx4 v[216:217], off
	v_lshl_add_u64 v[216:217], s[20:21], 0, v[190:191]
	s_mov_b32 m0, s34
	s_nop 0
	global_load_lds_dwordx4 v[216:217], off
	s_waitcnt vmcnt(8)
	s_waitcnt lgkmcnt(0)
	s_barrier
	s_setprio 1
	s_waitcnt lgkmcnt(0)
	v_mfma_f32_16x16x32_bf16 v[152:155], v[112:115], v[160:163], v[152:155]
	v_mfma_f32_16x16x32_bf16 v[148:151], v[120:123], v[160:163], v[148:151]
	v_mfma_f32_16x16x32_bf16 v[108:111], v[112:115], v[168:171], v[108:111]
	v_mfma_f32_16x16x32_bf16 v[104:107], v[120:123], v[168:171], v[104:107]
	v_mfma_f32_16x16x32_bf16 v[92:95], v[112:115], v[176:179], v[92:95]
	v_mfma_f32_16x16x32_bf16 v[88:91], v[120:123], v[176:179], v[88:91]
	v_mfma_f32_16x16x32_bf16 v[76:79], v[112:115], v[184:187], v[76:79]
	v_mfma_f32_16x16x32_bf16 v[72:75], v[120:123], v[184:187], v[72:75]
	v_mfma_f32_16x16x32_bf16 v[152:155], v[116:119], v[164:167], v[152:155]
	v_mfma_f32_16x16x32_bf16 v[148:151], v[128:131], v[164:167], v[148:151]
	v_mfma_f32_16x16x32_bf16 v[108:111], v[116:119], v[172:175], v[108:111]
	v_mfma_f32_16x16x32_bf16 v[104:107], v[128:131], v[172:175], v[104:107]
	v_mfma_f32_16x16x32_bf16 v[92:95], v[116:119], v[180:183], v[92:95]
	v_mfma_f32_16x16x32_bf16 v[88:91], v[128:131], v[180:183], v[88:91]
	v_mfma_f32_16x16x32_bf16 v[76:79], v[116:119], v[204:207], v[76:79]
	v_mfma_f32_16x16x32_bf16 v[72:75], v[128:131], v[204:207], v[72:75]
	v_mfma_f32_16x16x32_bf16 v[132:135], v[136:139], v[160:163], v[132:135]
	v_mfma_f32_16x16x32_bf16 v[124:127], v[144:147], v[160:163], v[124:127]
	v_mfma_f32_16x16x32_bf16 v[100:103], v[136:139], v[168:171], v[100:103]
	v_mfma_f32_16x16x32_bf16 v[96:99], v[144:147], v[168:171], v[96:99]
	v_mfma_f32_16x16x32_bf16 v[84:87], v[136:139], v[176:179], v[84:87]
	v_mfma_f32_16x16x32_bf16 v[80:83], v[144:147], v[176:179], v[80:83]
	v_mfma_f32_16x16x32_bf16 v[68:71], v[136:139], v[184:187], v[68:71]
	v_mfma_f32_16x16x32_bf16 v[64:67], v[144:147], v[184:187], v[64:67]
	v_mfma_f32_16x16x32_bf16 v[132:135], v[140:143], v[164:167], v[132:135]
	v_mfma_f32_16x16x32_bf16 v[124:127], v[156:159], v[164:167], v[124:127]
	v_mfma_f32_16x16x32_bf16 v[100:103], v[140:143], v[172:175], v[100:103]
	v_mfma_f32_16x16x32_bf16 v[96:99], v[156:159], v[172:175], v[96:99]
	v_mfma_f32_16x16x32_bf16 v[84:87], v[140:143], v[180:183], v[84:87]
	v_mfma_f32_16x16x32_bf16 v[80:83], v[156:159], v[180:183], v[80:83]
	v_mfma_f32_16x16x32_bf16 v[68:71], v[140:143], v[204:207], v[68:71]
	v_mfma_f32_16x16x32_bf16 v[64:67], v[156:159], v[204:207], v[64:67]
	s_setprio 0
	s_barrier
; #define PG8_STAGE(bufoff, gbase, voff) do { _Pragma("unroll") for (int _i = 0; _i < 2; ++_i) \
;         __builtin_amdgcn_global_load_lds((const unsigned*)((const char*)(gbase) + (voff)[_i]), (LAS unsigned*)(lds + (bufoff) + ldsw + _i * 8192), 16, 0, 0); } while (0)
; #define PG8_LDA(dst, b, h) do { _Pragma("unroll") for (int m = 0; m < 4; ++m) _Pragma("unroll") for (int k = 0; k < 2; ++k) dst[m][k] = *(const LAS bf16x8*)(lds + PG8_SA(b, h) + aoff + m * 2048 + k * 1024); } while (0)
; #define PG8_MMA(ai, bj, At, Bt) do { __builtin_amdgcn_s_setprio(1); _Pragma("unroll") for (int m = 0; m < 4; ++m) _Pragma("unroll") for (int n = 0; n < 2; ++n) _Pragma("unroll") for (int k = 0; k < 2; ++k) \
;         acc[ai][bj][m][n] = __builtin_amdgcn_mfma_f32_16x16x32_bf16(Bt[n][k], At[m][k], acc[ai][bj][m][n], 0, 0, 0); __builtin_amdgcn_s_setprio(0); } while (0)
; #define PG8_WAIT_V(n) asm volatile("s_waitcnt vmcnt(" #n ")" ::: "memory")
; #define PG8_WAIT_L(n) asm volatile("s_waitcnt lgkmcnt(" #n ")" ::: "memory")
; #define PG8_BAR __builtin_amdgcn_s_barrier()
; #define PG8_SCHED __builtin_amdgcn_sched_barrier(0)
; template <class Epi, class Sched, bool APERM = false, bool HALFN = false>
; __device__ __forceinline__ void gemm_phase(LAS unsigned char* lds, const int tid_in, const int K, const Sched& S, const Epi& E) {
;     ...
;             PG8_LDA(At, 1, 1); PG8_STAGE(PG8_SB(1, 0), b3, voffB); PG8_STAGE(PG8_SB(1, 1), b3 + hstep, voffB); PG8_STAGE(PG8_SA(1, 0), a3, voffA);
;             PG8_WAIT_V(8); PG8_WAIT_L(0); PG8_BAR; PG8_MMA(1, 0, At, B0); if constexpr (!HALFN) PG8_MMA(1, 1, At, B1); PG8_BAR; PG8_SCHED;
;         }
	s_add_i32 s20, s57, s28
	v_lshl_add_u64 v[208:209], v[208:209], 0, s[78:79]
	s_mov_b32 m0, s20
	ds_read_b128 v[160:163], v226 offset:49152
	ds_read_b128 v[164:167], v226 offset:50176
	ds_read_b128 v[168:171], v226 offset:51200
	ds_read_b128 v[172:175], v226 offset:52224
	ds_read_b128 v[176:179], v226 offset:53248
	ds_read_b128 v[180:183], v226 offset:54272
	ds_read_b128 v[184:187], v226 offset:55296
	ds_read_b128 v[204:207], v226 offset:56320
	global_load_lds_dwordx4 v[208:209], off
	s_add_i32 m0, s20, 0x2000
	s_add_u32 s18, s18, 0x20080
	v_lshl_add_u64 v[208:209], v[210:211], 0, s[78:79]
	s_addc_u32 s19, s19, 0
	s_add_i32 s20, s70, s28
	global_load_lds_dwordx4 v[208:209], off
	v_lshl_add_u64 v[208:209], s[18:19], 0, v[200:201]
	s_mov_b32 m0, s20
	s_nop 0
	global_load_lds_dwordx4 v[208:209], off
	v_lshl_add_u64 v[208:209], s[18:19], 0, v[192:193]
	s_add_i32 m0, s20, 0x2000
	s_nop 0
	global_load_lds_dwordx4 v[208:209], off
	v_lshl_add_u64 v[208:209], v[212:213], 0, s[78:79]
	s_mov_b32 m0, s35
	s_nop 0
	global_load_lds_dwordx4 v[208:209], off
	v_lshl_add_u64 v[208:209], v[214:215], 0, s[78:79]
	s_mov_b32 m0, s38
	s_nop 0
	global_load_lds_dwordx4 v[208:209], off
	s_waitcnt vmcnt(8)
	s_waitcnt lgkmcnt(0)
	s_barrier
	s_setprio 1
	s_waitcnt lgkmcnt(0)
	v_mfma_f32_16x16x32_bf16 v[60:63], v[112:115], v[160:163], v[60:63]
	v_mfma_f32_16x16x32_bf16 v[56:59], v[120:123], v[160:163], v[56:59]
	v_mfma_f32_16x16x32_bf16 v[44:47], v[112:115], v[168:171], v[44:47]
	v_mfma_f32_16x16x32_bf16 v[40:43], v[120:123], v[168:171], v[40:43]
	v_mfma_f32_16x16x32_bf16 v[28:31], v[112:115], v[176:179], v[28:31]
	v_mfma_f32_16x16x32_bf16 v[24:27], v[120:123], v[176:179], v[24:27]
	v_mfma_f32_16x16x32_bf16 v[12:15], v[112:115], v[184:187], v[12:15]
	v_mfma_f32_16x16x32_bf16 v[8:11], v[120:123], v[184:187], v[8:11]
	v_mfma_f32_16x16x32_bf16 v[60:63], v[116:119], v[164:167], v[60:63]
	v_mfma_f32_16x16x32_bf16 v[56:59], v[128:131], v[164:167], v[56:59]
	v_mfma_f32_16x16x32_bf16 v[44:47], v[116:119], v[172:175], v[44:47]
	v_mfma_f32_16x16x32_bf16 v[40:43], v[128:131], v[172:175], v[40:43]
	v_mfma_f32_16x16x32_bf16 v[28:31], v[116:119], v[180:183], v[28:31]
	v_mfma_f32_16x16x32_bf16 v[24:27], v[128:131], v[180:183], v[24:27]
	v_mfma_f32_16x16x32_bf16 v[12:15], v[116:119], v[204:207], v[12:15]
	v_mfma_f32_16x16x32_bf16 v[8:11], v[128:131], v[204:207], v[8:11]
	v_mfma_f32_16x16x32_bf16 v[52:55], v[136:139], v[160:163], v[52:55]
	v_mfma_f32_16x16x32_bf16 v[48:51], v[144:147], v[160:163], v[48:51]
	v_mfma_f32_16x16x32_bf16 v[36:39], v[136:139], v[168:171], v[36:39]
	v_mfma_f32_16x16x32_bf16 v[32:35], v[144:147], v[168:171], v[32:35]
	v_mfma_f32_16x16x32_bf16 v[20:23], v[136:139], v[176:179], v[20:23]
	v_mfma_f32_16x16x32_bf16 v[16:19], v[144:147], v[176:179], v[16:19]
	v_mfma_f32_16x16x32_bf16 v[4:7], v[136:139], v[184:187], v[4:7]
	v_mfma_f32_16x16x32_bf16 v[0:3], v[144:147], v[184:187], v[0:3]
	v_mfma_f32_16x16x32_bf16 v[52:55], v[140:143], v[164:167], v[52:55]
	v_mfma_f32_16x16x32_bf16 v[48:51], v[156:159], v[164:167], v[48:51]
	v_mfma_f32_16x16x32_bf16 v[36:39], v[140:143], v[172:175], v[36:39]
	v_mfma_f32_16x16x32_bf16 v[32:35], v[156:159], v[172:175], v[32:35]
	v_mfma_f32_16x16x32_bf16 v[20:23], v[140:143], v[180:183], v[20:23]
	v_mfma_f32_16x16x32_bf16 v[16:19], v[156:159], v[180:183], v[16:19]
	v_mfma_f32_16x16x32_bf16 v[4:7], v[140:143], v[204:207], v[4:7]
	v_mfma_f32_16x16x32_bf16 v[0:3], v[156:159], v[204:207], v[0:3]
	s_setprio 0
	s_barrier
	s_add_i32 s53, s53, 2
	s_add_u32 s45, s45, 0x100
	s_addc_u32 s52, s52, 0
	s_add_u32 s16, s16, 0x100
	s_addc_u32 s17, s17, 0
	s_cmp_gt_u32 s53, 5
	s_cbranch_scc0 .LBB0_806
	s_and_b64 vcc, exec, s[8:9]
	s_cbranch_vccz .LBB0_809
	s_barrier

; #define PG8_STAGE(bufoff, gbase, voff) do { _Pragma("unroll") for (int _i = 0; _i < 2; ++_i) \
;         __builtin_amdgcn_global_load_lds((const unsigned*)((const char*)(gbase) + (voff)[_i]), (LAS unsigned*)(lds + (bufoff) + ldsw + _i * 8192), 16, 0, 0); } while (0)
; #define PG8_LDA(dst, b, h) do { _Pragma("unroll") for (int m = 0; m < 4; ++m) _Pragma("unroll") for (int k = 0; k < 2; ++k) dst[m][k] = *(const LAS bf16x8*)(lds + PG8_SA(b, h) + aoff + m * 2048 + k * 1024); } while (0)
; #define PG8_LDB(dst, b, h) do { _Pragma("unroll") for (int n = 0; n < 2; ++n) _Pragma("unroll") for (int k = 0; k < 2; ++k) dst[n][k] = *(const LAS bf16x8*)(lds + PG8_SB(b, h) + boff + n * 2048 + k * 1024); } while (0)
; #define PG8_MMA(ai, bj, At, Bt) do { __builtin_amdgcn_s_setprio(1); _Pragma("unroll") for (int m = 0; m < 4; ++m) _Pragma("unroll") for (int n = 0; n < 2; ++n) _Pragma("unroll") for (int k = 0; k < 2; ++k) \
;         acc[ai][bj][m][n] = __builtin_amdgcn_mfma_f32_16x16x32_bf16(Bt[n][k], At[m][k], acc[ai][bj][m][n], 0, 0, 0); __builtin_amdgcn_s_setprio(0); } while (0)
; #define PG8_WAIT_V(n) asm volatile("s_waitcnt vmcnt(" #n ")" ::: "memory")
; #define PG8_WAIT_L(n) asm volatile("s_waitcnt lgkmcnt(" #n ")" ::: "memory")
; template <class Epi, class Sched, bool APERM = false, bool HALFN = false>
; __device__ __forceinline__ void gemm_phase(LAS unsigned char* lds, const int tid_in, const int K, const Sched& S, const Epi& E) {
;     ...
;         for (int t = 0; t < nt; t += 2) {
;             const bool last = (t == nt - 2);
;             const char* a1 = cA + (size_t)(t + 1) * kstep;
;             const char* a2 = last ? nA : cA + (size_t)(t + 2) * kstep; const char* b2 = last ? nB : cB + (size_t)(t + 2) * kstep;
;             const char* a3 = a2 + kstep; const char* b3 = b2 + kstep;
;             PG8_LDB(B0, 0, 0); PG8_LDB(B1, 0, 1); PG8_SCHED; PG8_LDA(At, 0, 0); PG8_STAGE(PG8_SA(1, 1), a1 + hstepA, voffA);
;             PG8_WAIT_V(8); PG8_WAIT_L(0); PG8_BAR; PG8_MMA(0, 0, At, B0); if constexpr (!HALFN) PG8_MMA(0, 1, At, B1); PG8_BAR; PG8_SCHED;
;             PG8_LDA(At, 0, 1); PG8_STAGE(PG8_SB(0, 0), b2, voffB); PG8_STAGE(PG8_SB(0, 1), b2 + hstep, voffB); PG8_STAGE(PG8_SA(0, 0), a2, voffA);
;             PG8_WAIT_V(8); PG8_WAIT_L(0); PG8_BAR; PG8_MMA(1, 0, At, B0); if constexpr (!HALFN) PG8_MMA(1, 1, At, B1); PG8_BAR; PG8_SCHED;
.LBB0_902:
	s_add_u32 s4, s0, 0x100
	s_addc_u32 s5, s1, 0
	s_add_i32 s14, 0, 0x10000
	s_cmp_eq_u32 s13, 28
	s_cselect_b32 s9, s23, s5
	s_cselect_b32 s8, s22, s4
	v_add_u32_e32 v52, s14, v202
	s_cselect_b32 s7, s25, s12
	s_cselect_b32 s6, s24, s11
	s_add_i32 s15, 0, 0x14000
	ds_read_b128 v[62:65], v52
	ds_read_b128 v[128:131], v52 offset:1024
	ds_read_b128 v[132:135], v52 offset:2048
	ds_read_b128 v[136:139], v52 offset:3072
	v_add_u32_e32 v52, s15, v202
	ds_read_b128 v[140:143], v52
	ds_read_b128 v[152:155], v52 offset:1024
	ds_read_b128 v[156:159], v52 offset:2048
	ds_read_b128 v[160:163], v52 offset:3072
	v_lshl_add_u64 v[52:53], s[0:1], 0, v[214:215]
	s_add_i32 m0, s57, 0xc000
	ds_read_b128 v[164:167], v243
	ds_read_b128 v[168:171], v243 offset:1024
	ds_read_b128 v[172:175], v243 offset:2048
	ds_read_b128 v[176:179], v243 offset:3072
	ds_read_b128 v[180:183], v243 offset:4096
	ds_read_b128 v[184:187], v243 offset:5120
	ds_read_b128 v[188:191], v243 offset:6144
	ds_read_b128 v[192:195], v243 offset:7168
	global_load_lds_dwordx4 v[52:53], off
	v_lshl_add_u64 v[52:53], s[0:1], 0, v[212:213]
	s_add_i32 m0, s57, 0xe000
	s_nop 0
	global_load_lds_dwordx4 v[52:53], off
	s_waitcnt vmcnt(8)
	s_waitcnt lgkmcnt(0)
	s_barrier
	s_setprio 1
	s_waitcnt lgkmcnt(0)
	v_mfma_f32_16x16x32_bf16 v[148:151], v[62:65], v[164:167], v[148:151]
	v_mfma_f32_16x16x32_bf16 v[58:61], v[132:135], v[164:167], v[58:61]
	v_mfma_f32_16x16x32_bf16 v[124:127], v[62:65], v[172:175], v[124:127]
	v_mfma_f32_16x16x32_bf16 v[36:39], v[132:135], v[172:175], v[36:39]
	v_mfma_f32_16x16x32_bf16 v[116:119], v[62:65], v[180:183], v[116:119]
	v_mfma_f32_16x16x32_bf16 v[28:31], v[132:135], v[180:183], v[28:31]
	v_mfma_f32_16x16x32_bf16 v[108:111], v[62:65], v[188:191], v[108:111]
	v_mfma_f32_16x16x32_bf16 v[20:23], v[132:135], v[188:191], v[20:23]
	v_mfma_f32_16x16x32_bf16 v[148:151], v[128:131], v[168:171], v[148:151]
	v_mfma_f32_16x16x32_bf16 v[58:61], v[136:139], v[168:171], v[58:61]
	v_mfma_f32_16x16x32_bf16 v[124:127], v[128:131], v[176:179], v[124:127]
	v_mfma_f32_16x16x32_bf16 v[36:39], v[136:139], v[176:179], v[36:39]
	v_mfma_f32_16x16x32_bf16 v[116:119], v[128:131], v[184:187], v[116:119]
	v_mfma_f32_16x16x32_bf16 v[28:31], v[136:139], v[184:187], v[28:31]
	v_mfma_f32_16x16x32_bf16 v[108:111], v[128:131], v[192:195], v[108:111]
	v_mfma_f32_16x16x32_bf16 v[20:23], v[136:139], v[192:195], v[20:23]
	v_mfma_f32_16x16x32_bf16 v[144:147], v[140:143], v[164:167], v[144:147]
	v_mfma_f32_16x16x32_bf16 v[40:43], v[156:159], v[164:167], v[40:43]
	v_mfma_f32_16x16x32_bf16 v[120:123], v[140:143], v[172:175], v[120:123]
	v_mfma_f32_16x16x32_bf16 v[32:35], v[156:159], v[172:175], v[32:35]
	v_mfma_f32_16x16x32_bf16 v[112:115], v[140:143], v[180:183], v[112:115]
	v_mfma_f32_16x16x32_bf16 v[24:27], v[156:159], v[180:183], v[24:27]
	v_mfma_f32_16x16x32_bf16 v[104:107], v[140:143], v[188:191], v[104:107]
	v_mfma_f32_16x16x32_bf16 v[16:19], v[156:159], v[188:191], v[16:19]
	v_mfma_f32_16x16x32_bf16 v[144:147], v[152:155], v[168:171], v[144:147]
	v_mfma_f32_16x16x32_bf16 v[40:43], v[160:163], v[168:171], v[40:43]
	v_mfma_f32_16x16x32_bf16 v[120:123], v[152:155], v[176:179], v[120:123]
	v_mfma_f32_16x16x32_bf16 v[32:35], v[160:163], v[176:179], v[32:35]
	v_mfma_f32_16x16x32_bf16 v[112:115], v[152:155], v[184:187], v[112:115]
	v_mfma_f32_16x16x32_bf16 v[24:27], v[160:163], v[184:187], v[24:27]
	v_mfma_f32_16x16x32_bf16 v[104:107], v[152:155], v[192:195], v[104:107]
	v_mfma_f32_16x16x32_bf16 v[16:19], v[160:163], v[192:195], v[16:19]
	s_setprio 0
	s_barrier
	s_add_i32 s0, s14, s39
	v_lshl_add_u64 v[196:197], s[6:7], 0, v[206:207]
	s_mov_b32 m0, s0
	ds_read_b128 v[164:167], v243 offset:16384
	ds_read_b128 v[168:171], v243 offset:17408
	ds_read_b128 v[172:175], v243 offset:18432
	ds_read_b128 v[176:179], v243 offset:19456
	ds_read_b128 v[180:183], v243 offset:20480
	ds_read_b128 v[184:187], v243 offset:21504
	ds_read_b128 v[188:191], v243 offset:22528
	ds_read_b128 v[192:195], v243 offset:23552
	global_load_lds_dwordx4 v[196:197], off
	s_add_i32 m0, s0, 0x2000
	s_add_u32 s0, s6, 0x80000
	v_lshl_add_u64 v[198:199], s[6:7], 0, v[210:211]
	s_addc_u32 s1, s7, 0
	s_add_i32 s14, s15, s39
	global_load_lds_dwordx4 v[198:199], off
	v_lshl_add_u64 v[52:53], s[0:1], 0, v[206:207]
	s_mov_b32 m0, s14
	v_lshl_add_u64 v[216:217], s[8:9], 0, v[204:205]
	global_load_lds_dwordx4 v[52:53], off
	v_lshl_add_u64 v[52:53], s[0:1], 0, v[210:211]
	s_add_i32 m0, s14, 0x2000
	v_lshl_add_u64 v[218:219], s[8:9], 0, v[208:209]
	global_load_lds_dwordx4 v[52:53], off
	s_mov_b32 m0, s57
	s_nop 0
	global_load_lds_dwordx4 v[216:217], off
	s_mov_b32 m0, s70
	s_nop 0
	global_load_lds_dwordx4 v[218:219], off
	s_waitcnt vmcnt(8)
	s_waitcnt lgkmcnt(0)
	s_barrier
; #define PG8_STAGE(bufoff, gbase, voff) do { _Pragma("unroll") for (int _i = 0; _i < 2; ++_i) \
;         __builtin_amdgcn_global_load_lds((const unsigned*)((const char*)(gbase) + (voff)[_i]), (LAS unsigned*)(lds + (bufoff) + ldsw + _i * 8192), 16, 0, 0); } while (0)
; #define PG8_LDA(dst, b, h) do { _Pragma("unroll") for (int m = 0; m < 4; ++m) _Pragma("unroll") for (int k = 0; k < 2; ++k) dst[m][k] = *(const LAS bf16x8*)(lds + PG8_SA(b, h) + aoff + m * 2048 + k * 1024); } while (0)
; #define PG8_LDB(dst, b, h) do { _Pragma("unroll") for (int n = 0; n < 2; ++n) _Pragma("unroll") for (int k = 0; k < 2; ++k) dst[n][k] = *(const LAS bf16x8*)(lds + PG8_SB(b, h) + boff + n * 2048 + k * 1024); } while (0)
; #define PG8_MMA(ai, bj, At, Bt) do { __builtin_amdgcn_s_setprio(1); _Pragma("unroll") for (int m = 0; m < 4; ++m) _Pragma("unroll") for (int n = 0; n < 2; ++n) _Pragma("unroll") for (int k = 0; k < 2; ++k) \
;         acc[ai][bj][m][n] = __builtin_amdgcn_mfma_f32_16x16x32_bf16(Bt[n][k], At[m][k], acc[ai][bj][m][n], 0, 0, 0); __builtin_amdgcn_s_setprio(0); } while (0)
; #define PG8_WAIT_V(n) asm volatile("s_waitcnt vmcnt(" #n ")" ::: "memory")
; #define PG8_WAIT_L(n) asm volatile("s_waitcnt lgkmcnt(" #n ")" ::: "memory")
; #define PG8_BAR __builtin_amdgcn_s_barrier()
; #define PG8_SCHED __builtin_amdgcn_sched_barrier(0)
; template <class Epi, class Sched, bool APERM = false, bool HALFN = false>
; __device__ __forceinline__ void gemm_phase(LAS unsigned char* lds, const int tid_in, const int K, const Sched& S, const Epi& E) {
;     ...
;             PG8_WAIT_V(8); PG8_WAIT_L(0); PG8_BAR; PG8_MMA(1, 0, At, B0); if constexpr (!HALFN) PG8_MMA(1, 1, At, B1); PG8_BAR; PG8_SCHED;
;             PG8_LDB(B0, 1, 0); PG8_LDB(B1, 1, 1); PG8_SCHED; PG8_LDA(At, 1, 0); PG8_STAGE(PG8_SA(0, 1), a2 + hstepA, voffA);
;             PG8_WAIT_V(8); PG8_WAIT_L(0); PG8_BAR; PG8_MMA(0, 0, At, B0); if constexpr (!HALFN) PG8_MMA(0, 1, At, B1); PG8_BAR; PG8_SCHED;
;             PG8_LDA(At, 1, 1); PG8_STAGE(PG8_SB(1, 0), b3, voffB); PG8_STAGE(PG8_SB(1, 1), b3 + hstep, voffB); PG8_STAGE(PG8_SA(1, 0), a3, voffA);
	s_setprio 1
	s_waitcnt lgkmcnt(0)
	v_mfma_f32_16x16x32_bf16 v[100:103], v[62:65], v[164:167], v[100:103]
	v_mfma_f32_16x16x32_bf16 v[12:15], v[132:135], v[164:167], v[12:15]
	v_mfma_f32_16x16x32_bf16 v[92:95], v[62:65], v[172:175], v[92:95]
	v_mfma_f32_16x16x32_bf16 v[4:7], v[132:135], v[172:175], v[4:7]
	v_mfma_f32_16x16x32_bf16 v[48:51], v[62:65], v[180:183], v[48:51]
	v_mfma_f32_16x16x32_bf16 v[72:75], v[132:135], v[180:183], v[72:75]
	v_mfma_f32_16x16x32_bf16 v[66:69], v[132:135], v[188:191], v[68:71]
	v_mfma_f32_16x16x32_bf16 v[100:103], v[128:131], v[168:171], v[100:103]
	v_mfma_f32_16x16x32_bf16 v[12:15], v[136:139], v[168:171], v[12:15]
	v_mfma_f32_16x16x32_bf16 v[92:95], v[128:131], v[176:179], v[92:95]
	v_mfma_f32_16x16x32_bf16 v[4:7], v[136:139], v[176:179], v[4:7]
	v_mfma_f32_16x16x32_bf16 v[48:51], v[128:131], v[184:187], v[48:51]
	v_mfma_f32_16x16x32_bf16 v[72:75], v[136:139], v[184:187], v[72:75]
	v_mfma_f32_16x16x32_bf16 v[62:65], v[62:65], v[188:191], v[80:83]
	v_mfma_f32_16x16x32_bf16 v[66:69], v[136:139], v[192:195], v[66:69]
	v_mfma_f32_16x16x32_bf16 v[62:65], v[128:131], v[192:195], v[62:65]
	v_mfma_f32_16x16x32_bf16 v[80:83], v[140:143], v[164:167], v[96:99]
	v_mfma_f32_16x16x32_bf16 v[96:99], v[152:155], v[168:171], v[80:83]
	v_mfma_f32_16x16x32_bf16 v[80:83], v[140:143], v[172:175], v[88:91]
	v_mfma_f32_16x16x32_bf16 v[8:11], v[156:159], v[164:167], v[8:11]
	v_mfma_f32_16x16x32_bf16 v[88:91], v[152:155], v[176:179], v[80:83]
	v_mfma_f32_16x16x32_bf16 v[0:3], v[156:159], v[172:175], v[0:3]
	v_mfma_f32_16x16x32_bf16 v[80:83], v[140:143], v[180:183], v[84:87]
	v_mfma_f32_16x16x32_bf16 v[52:55], v[156:159], v[180:183], v[54:57]
	v_mfma_f32_16x16x32_bf16 v[76:79], v[140:143], v[188:191], v[76:79]
	v_mfma_f32_16x16x32_bf16 v[44:47], v[156:159], v[188:191], v[44:47]
	v_mfma_f32_16x16x32_bf16 v[8:11], v[160:163], v[168:171], v[8:11]
	v_mfma_f32_16x16x32_bf16 v[0:3], v[160:163], v[176:179], v[0:3]
	v_mfma_f32_16x16x32_bf16 v[84:87], v[152:155], v[184:187], v[80:83]
	v_mfma_f32_16x16x32_bf16 v[52:55], v[160:163], v[184:187], v[52:55]
	v_mfma_f32_16x16x32_bf16 v[76:79], v[152:155], v[192:195], v[76:79]
	v_mfma_f32_16x16x32_bf16 v[44:47], v[160:163], v[192:195], v[44:47]
	s_setprio 0
	s_barrier
	s_add_i32 s14, 0, 0x18000
	v_add_u32_e32 v56, s14, v202
	s_add_i32 s15, 0, 0x1c000
	ds_read_b128 v[80:83], v56
	ds_read_b128 v[128:131], v56 offset:1024
	ds_read_b128 v[132:135], v56 offset:2048
	ds_read_b128 v[136:139], v56 offset:3072
	v_add_u32_e32 v56, s15, v202
	ds_read_b128 v[140:143], v56
	ds_read_b128 v[152:155], v56 offset:1024
	ds_read_b128 v[156:159], v56 offset:2048
	ds_read_b128 v[160:163], v56 offset:3072
	s_add_u32 s0, s8, 0x4000
	s_addc_u32 s1, s9, 0
	s_mov_b32 m0, s71
	v_lshl_add_u64 v[56:57], s[0:1], 0, v[204:205]
	ds_read_b128 v[164:167], v243 offset:32768
	ds_read_b128 v[168:171], v243 offset:33792
	ds_read_b128 v[172:175], v243 offset:34816
	ds_read_b128 v[176:179], v243 offset:35840
	ds_read_b128 v[180:183], v243 offset:36864
	ds_read_b128 v[184:187], v243 offset:37888
	ds_read_b128 v[188:191], v243 offset:38912
	ds_read_b128 v[192:195], v243 offset:39936
	global_load_lds_dwordx4 v[56:57], off
	v_lshl_add_u64 v[56:57], s[0:1], 0, v[208:209]
	s_mov_b32 m0, s72
	s_nop 0
	global_load_lds_dwordx4 v[56:57], off
	s_waitcnt vmcnt(8)
	s_waitcnt lgkmcnt(0)
	s_barrier
	s_setprio 1
	s_waitcnt lgkmcnt(0)
	v_mfma_f32_16x16x32_bf16 v[148:151], v[80:83], v[164:167], v[148:151]
	v_mfma_f32_16x16x32_bf16 v[56:59], v[132:135], v[164:167], v[58:61]
	v_mfma_f32_16x16x32_bf16 v[124:127], v[80:83], v[172:175], v[124:127]
	v_mfma_f32_16x16x32_bf16 v[36:39], v[132:135], v[172:175], v[36:39]
	v_mfma_f32_16x16x32_bf16 v[116:119], v[80:83], v[180:183], v[116:119]
	v_mfma_f32_16x16x32_bf16 v[28:31], v[132:135], v[180:183], v[28:31]
	v_mfma_f32_16x16x32_bf16 v[108:111], v[80:83], v[188:191], v[108:111]
	v_mfma_f32_16x16x32_bf16 v[20:23], v[132:135], v[188:191], v[20:23]
	v_mfma_f32_16x16x32_bf16 v[148:151], v[128:131], v[168:171], v[148:151]
	v_mfma_f32_16x16x32_bf16 v[58:61], v[136:139], v[168:171], v[56:59]
	v_mfma_f32_16x16x32_bf16 v[124:127], v[128:131], v[176:179], v[124:127]
	v_mfma_f32_16x16x32_bf16 v[36:39], v[136:139], v[176:179], v[36:39]
	v_mfma_f32_16x16x32_bf16 v[116:119], v[128:131], v[184:187], v[116:119]
	v_mfma_f32_16x16x32_bf16 v[28:31], v[136:139], v[184:187], v[28:31]
	v_mfma_f32_16x16x32_bf16 v[108:111], v[128:131], v[192:195], v[108:111]
	v_mfma_f32_16x16x32_bf16 v[20:23], v[136:139], v[192:195], v[20:23]
	v_mfma_f32_16x16x32_bf16 v[144:147], v[140:143], v[164:167], v[144:147]
	v_mfma_f32_16x16x32_bf16 v[40:43], v[156:159], v[164:167], v[40:43]
	v_mfma_f32_16x16x32_bf16 v[120:123], v[140:143], v[172:175], v[120:123]
	v_mfma_f32_16x16x32_bf16 v[32:35], v[156:159], v[172:175], v[32:35]
	v_mfma_f32_16x16x32_bf16 v[112:115], v[140:143], v[180:183], v[112:115]
	v_mfma_f32_16x16x32_bf16 v[24:27], v[156:159], v[180:183], v[24:27]
	v_mfma_f32_16x16x32_bf16 v[104:107], v[140:143], v[188:191], v[104:107]
	v_mfma_f32_16x16x32_bf16 v[16:19], v[156:159], v[188:191], v[16:19]
	v_mfma_f32_16x16x32_bf16 v[144:147], v[152:155], v[168:171], v[144:147]
	v_mfma_f32_16x16x32_bf16 v[40:43], v[160:163], v[168:171], v[40:43]
	v_mfma_f32_16x16x32_bf16 v[120:123], v[152:155], v[176:179], v[120:123]
	v_mfma_f32_16x16x32_bf16 v[32:35], v[160:163], v[176:179], v[32:35]
	v_mfma_f32_16x16x32_bf16 v[112:115], v[152:155], v[184:187], v[112:115]
	v_mfma_f32_16x16x32_bf16 v[24:27], v[160:163], v[184:187], v[24:27]
	v_mfma_f32_16x16x32_bf16 v[104:107], v[152:155], v[192:195], v[104:107]
	v_mfma_f32_16x16x32_bf16 v[16:19], v[160:163], v[192:195], v[16:19]
	s_setprio 0
	s_barrier
; #define PG8_STAGE(bufoff, gbase, voff) do { _Pragma("unroll") for (int _i = 0; _i < 2; ++_i) \
;         __builtin_amdgcn_global_load_lds((const unsigned*)((const char*)(gbase) + (voff)[_i]), (LAS unsigned*)(lds + (bufoff) + ldsw + _i * 8192), 16, 0, 0); } while (0)
; #define PG8_LDA(dst, b, h) do { _Pragma("unroll") for (int m = 0; m < 4; ++m) _Pragma("unroll") for (int k = 0; k < 2; ++k) dst[m][k] = *(const LAS bf16x8*)(lds + PG8_SA(b, h) + aoff + m * 2048 + k * 1024); } while (0)
; #define PG8_MMA(ai, bj, At, Bt) do { __builtin_amdgcn_s_setprio(1); _Pragma("unroll") for (int m = 0; m < 4; ++m) _Pragma("unroll") for (int n = 0; n < 2; ++n) _Pragma("unroll") for (int k = 0; k < 2; ++k) \
;         acc[ai][bj][m][n] = __builtin_amdgcn_mfma_f32_16x16x32_bf16(Bt[n][k], At[m][k], acc[ai][bj][m][n], 0, 0, 0); __builtin_amdgcn_s_setprio(0); } while (0)
; #define PG8_WAIT_V(n) asm volatile("s_waitcnt vmcnt(" #n ")" ::: "memory")
; #define PG8_WAIT_L(n) asm volatile("s_waitcnt lgkmcnt(" #n ")" ::: "memory")
; #define PG8_BAR __builtin_amdgcn_s_barrier()
; #define PG8_SCHED __builtin_amdgcn_sched_barrier(0)
; template <class Epi, class Sched, bool APERM = false, bool HALFN = false>
; __device__ __forceinline__ void gemm_phase(LAS unsigned char* lds, const int tid_in, const int K, const Sched& S, const Epi& E) {
;     ...
;             PG8_LDA(At, 1, 1); PG8_STAGE(PG8_SB(1, 0), b3, voffB); PG8_STAGE(PG8_SB(1, 1), b3 + hstep, voffB); PG8_STAGE(PG8_SA(1, 0), a3, voffA);
;             PG8_WAIT_V(8); PG8_WAIT_L(0); PG8_BAR; PG8_MMA(1, 0, At, B0); if constexpr (!HALFN) PG8_MMA(1, 1, At, B1); PG8_BAR; PG8_SCHED;
;         }
	s_add_i32 s0, s14, s39
	v_lshl_add_u64 v[56:57], v[196:197], 0, s[78:79]
	s_mov_b32 m0, s0
	ds_read_b128 v[164:167], v243 offset:49152
	ds_read_b128 v[168:171], v243 offset:50176
	ds_read_b128 v[172:175], v243 offset:51200
	ds_read_b128 v[176:179], v243 offset:52224
	ds_read_b128 v[180:183], v243 offset:53248
	ds_read_b128 v[184:187], v243 offset:54272
	ds_read_b128 v[188:191], v243 offset:55296
	ds_read_b128 v[192:195], v243 offset:56320
	global_load_lds_dwordx4 v[56:57], off
	s_add_i32 m0, s0, 0x2000
	s_add_u32 s0, s6, 0x80080
	v_lshl_add_u64 v[56:57], v[198:199], 0, s[78:79]
	s_addc_u32 s1, s7, 0
	s_add_i32 s6, s15, s39
	global_load_lds_dwordx4 v[56:57], off
	v_lshl_add_u64 v[56:57], s[0:1], 0, v[206:207]
	s_mov_b32 m0, s6
	s_nop 0
	global_load_lds_dwordx4 v[56:57], off
	v_lshl_add_u64 v[56:57], s[0:1], 0, v[210:211]
	s_add_i32 m0, s6, 0x2000
	s_nop 0
	global_load_lds_dwordx4 v[56:57], off
	v_lshl_add_u64 v[56:57], v[216:217], 0, s[78:79]
	s_mov_b32 m0, s81
	s_nop 0
	global_load_lds_dwordx4 v[56:57], off
	v_lshl_add_u64 v[56:57], v[218:219], 0, s[78:79]
	s_mov_b32 m0, s86
	s_nop 0
	global_load_lds_dwordx4 v[56:57], off
	s_waitcnt vmcnt(8)
	s_waitcnt lgkmcnt(0)
	s_barrier
	s_setprio 1
	s_waitcnt lgkmcnt(0)
	v_mfma_f32_16x16x32_bf16 v[62:65], v[80:83], v[188:191], v[62:65]
	v_mfma_f32_16x16x32_bf16 v[100:103], v[80:83], v[164:167], v[100:103]
	v_mfma_f32_16x16x32_bf16 v[12:15], v[132:135], v[164:167], v[12:15]
	v_mfma_f32_16x16x32_bf16 v[92:95], v[80:83], v[172:175], v[92:95]
	v_mfma_f32_16x16x32_bf16 v[4:7], v[132:135], v[172:175], v[4:7]
	v_mfma_f32_16x16x32_bf16 v[48:51], v[80:83], v[180:183], v[48:51]
	v_mfma_f32_16x16x32_bf16 v[70:73], v[132:135], v[180:183], v[72:75]
	v_mfma_f32_16x16x32_bf16 v[80:83], v[128:131], v[192:195], v[62:65]
	v_mfma_f32_16x16x32_bf16 v[62:65], v[132:135], v[188:191], v[66:69]
	v_mfma_f32_16x16x32_bf16 v[100:103], v[128:131], v[168:171], v[100:103]
	v_mfma_f32_16x16x32_bf16 v[12:15], v[136:139], v[168:171], v[12:15]
	v_mfma_f32_16x16x32_bf16 v[92:95], v[128:131], v[176:179], v[92:95]
	v_mfma_f32_16x16x32_bf16 v[4:7], v[136:139], v[176:179], v[4:7]
	v_mfma_f32_16x16x32_bf16 v[48:51], v[128:131], v[184:187], v[48:51]
	v_mfma_f32_16x16x32_bf16 v[72:75], v[136:139], v[184:187], v[70:73]
	v_mfma_f32_16x16x32_bf16 v[68:71], v[136:139], v[192:195], v[62:65]
	v_mfma_f32_16x16x32_bf16 v[62:65], v[140:143], v[164:167], v[96:99]
	v_mfma_f32_16x16x32_bf16 v[96:99], v[152:155], v[168:171], v[62:65]
	v_mfma_f32_16x16x32_bf16 v[62:65], v[140:143], v[172:175], v[88:91]
	v_mfma_f32_16x16x32_bf16 v[88:91], v[152:155], v[176:179], v[62:65]
	v_mfma_f32_16x16x32_bf16 v[62:65], v[140:143], v[180:183], v[84:87]
	v_mfma_f32_16x16x32_bf16 v[8:11], v[156:159], v[164:167], v[8:11]
	v_mfma_f32_16x16x32_bf16 v[0:3], v[156:159], v[172:175], v[0:3]
	v_mfma_f32_16x16x32_bf16 v[84:87], v[152:155], v[184:187], v[62:65]
	v_mfma_f32_16x16x32_bf16 v[52:55], v[156:159], v[180:183], v[52:55]
	v_mfma_f32_16x16x32_bf16 v[62:65], v[140:143], v[188:191], v[76:79]
	v_mfma_f32_16x16x32_bf16 v[44:47], v[156:159], v[188:191], v[44:47]
	v_mfma_f32_16x16x32_bf16 v[8:11], v[160:163], v[168:171], v[8:11]
	v_mfma_f32_16x16x32_bf16 v[0:3], v[160:163], v[176:179], v[0:3]
	v_mfma_f32_16x16x32_bf16 v[54:57], v[160:163], v[184:187], v[52:55]
	v_mfma_f32_16x16x32_bf16 v[76:79], v[152:155], v[192:195], v[62:65]
	v_mfma_f32_16x16x32_bf16 v[44:47], v[160:163], v[192:195], v[44:47]
	s_setprio 0
	s_barrier
	s_add_i32 s13, s13, 2
	s_add_u32 s11, s11, 0x100
	s_addc_u32 s12, s12, 0
	s_cmp_gt_u32 s13, 29
	s_mov_b64 s[0:1], s[4:5]
	s_cbranch_scc0 .LBB0_902
	s_and_b64 vcc, exec, s[16:17]
	s_cbranch_vccz .LBB0_905
	s_barrier

; #define PG8_STAGE(bufoff, gbase, voff) do { _Pragma("unroll") for (int _i = 0; _i < 2; ++_i) \
;         __builtin_amdgcn_global_load_lds((const unsigned*)((const char*)(gbase) + (voff)[_i]), (LAS unsigned*)(lds + (bufoff) + ldsw + _i * 8192), 16, 0, 0); } while (0)
; #define PG8_LDA(dst, b, h) do { _Pragma("unroll") for (int m = 0; m < 4; ++m) _Pragma("unroll") for (int k = 0; k < 2; ++k) dst[m][k] = *(const LAS bf16x8*)(lds + PG8_SA(b, h) + aoff + m * 2048 + k * 1024); } while (0)
; #define PG8_LDB(dst, b, h) do { _Pragma("unroll") for (int n = 0; n < 2; ++n) _Pragma("unroll") for (int k = 0; k < 2; ++k) dst[n][k] = *(const LAS bf16x8*)(lds + PG8_SB(b, h) + boff + n * 2048 + k * 1024); } while (0)
; #define PG8_MMA(ai, bj, At, Bt) do { __builtin_amdgcn_s_setprio(1); _Pragma("unroll") for (int m = 0; m < 4; ++m) _Pragma("unroll") for (int n = 0; n < 2; ++n) _Pragma("unroll") for (int k = 0; k < 2; ++k) \
;         acc[ai][bj][m][n] = __builtin_amdgcn_mfma_f32_16x16x32_bf16(Bt[n][k], At[m][k], acc[ai][bj][m][n], 0, 0, 0); __builtin_amdgcn_s_setprio(0); } while (0)
; #define PG8_WAIT_V(n) asm volatile("s_waitcnt vmcnt(" #n ")" ::: "memory")
; #define PG8_WAIT_L(n) asm volatile("s_waitcnt lgkmcnt(" #n ")" ::: "memory")
; template <class Epi, class Sched, bool APERM = false, bool HALFN = false>
; __device__ __forceinline__ void gemm_phase(LAS unsigned char* lds, const int tid_in, const int K, const Sched& S, const Epi& E) {
;     ...
;         for (int t = 0; t < nt; t += 2) {
;             const bool last = (t == nt - 2);
;             const char* a1 = cA + (size_t)(t + 1) * kstep;
;             const char* a2 = last ? nA : cA + (size_t)(t + 2) * kstep; const char* b2 = last ? nB : cB + (size_t)(t + 2) * kstep;
;             const char* a3 = a2 + kstep; const char* b3 = b2 + kstep;
;             PG8_LDB(B0, 0, 0); PG8_LDB(B1, 0, 1); PG8_SCHED; PG8_LDA(At, 0, 0); PG8_STAGE(PG8_SA(1, 1), a1 + hstepA, voffA);
;             PG8_WAIT_V(8); PG8_WAIT_L(0); PG8_BAR; PG8_MMA(0, 0, At, B0); if constexpr (!HALFN) PG8_MMA(0, 1, At, B1); PG8_BAR; PG8_SCHED;
;             PG8_LDA(At, 0, 1); PG8_STAGE(PG8_SB(0, 0), b2, voffB); PG8_STAGE(PG8_SB(0, 1), b2 + hstep, voffB); PG8_STAGE(PG8_SA(0, 0), a2, voffA);
;             PG8_WAIT_V(8); PG8_WAIT_L(0); PG8_BAR; PG8_MMA(1, 0, At, B0); if constexpr (!HALFN) PG8_MMA(1, 1, At, B1); PG8_BAR; PG8_SCHED;
.LBB0_1033:
	s_add_u32 s18, s16, 0x100
	s_addc_u32 s19, s17, 0
	s_add_i32 s71, 0, 0x10000
	s_cmpk_eq_i32 s70, 0x54
	s_cselect_b32 s23, s11, s19
	s_cselect_b32 s22, s10, s18
	s_cselect_b32 s21, s13, s57
	s_cselect_b32 s20, s12, s53
	s_add_i32 s72, 0, 0x14000
	v_add_u32_e32 v128, s71, v220
	v_add_u32_e32 v156, s72, v220
	ds_read_b128 v[112:115], v128
	ds_read_b128 v[116:119], v128 offset:1024
	ds_read_b128 v[120:123], v128 offset:2048
	ds_read_b128 v[128:131], v128 offset:3072
	ds_read_b128 v[136:139], v156
	ds_read_b128 v[140:143], v156 offset:1024
	ds_read_b128 v[144:147], v156 offset:2048
	ds_read_b128 v[156:159], v156 offset:3072
	v_lshl_add_u64 v[208:209], s[16:17], 0, v[198:199]
	s_add_i32 m0, s31, 0xc000
	ds_read_b128 v[160:163], v226
	ds_read_b128 v[164:167], v226 offset:1024
	ds_read_b128 v[168:171], v226 offset:2048
	ds_read_b128 v[172:175], v226 offset:3072
	ds_read_b128 v[176:179], v226 offset:4096
	ds_read_b128 v[180:183], v226 offset:5120
	ds_read_b128 v[184:187], v226 offset:6144
	ds_read_b128 v[204:207], v226 offset:7168
	global_load_lds_dwordx4 v[208:209], off
	v_lshl_add_u64 v[208:209], s[16:17], 0, v[196:197]
	s_add_i32 m0, s31, 0xe000
	s_nop 0
	global_load_lds_dwordx4 v[208:209], off
	s_waitcnt vmcnt(8)
	s_waitcnt lgkmcnt(0)
	s_barrier
	s_setprio 1
	s_waitcnt lgkmcnt(0)
	v_mfma_f32_16x16x32_bf16 v[152:155], v[112:115], v[160:163], v[152:155]
	v_mfma_f32_16x16x32_bf16 v[148:151], v[120:123], v[160:163], v[148:151]
	v_mfma_f32_16x16x32_bf16 v[108:111], v[112:115], v[168:171], v[108:111]
	v_mfma_f32_16x16x32_bf16 v[104:107], v[120:123], v[168:171], v[104:107]
	v_mfma_f32_16x16x32_bf16 v[92:95], v[112:115], v[176:179], v[92:95]
	v_mfma_f32_16x16x32_bf16 v[88:91], v[120:123], v[176:179], v[88:91]
	v_mfma_f32_16x16x32_bf16 v[76:79], v[112:115], v[184:187], v[76:79]
	v_mfma_f32_16x16x32_bf16 v[72:75], v[120:123], v[184:187], v[72:75]
	v_mfma_f32_16x16x32_bf16 v[152:155], v[116:119], v[164:167], v[152:155]
	v_mfma_f32_16x16x32_bf16 v[148:151], v[128:131], v[164:167], v[148:151]
	v_mfma_f32_16x16x32_bf16 v[108:111], v[116:119], v[172:175], v[108:111]
	v_mfma_f32_16x16x32_bf16 v[104:107], v[128:131], v[172:175], v[104:107]
	v_mfma_f32_16x16x32_bf16 v[92:95], v[116:119], v[180:183], v[92:95]
	v_mfma_f32_16x16x32_bf16 v[88:91], v[128:131], v[180:183], v[88:91]
	v_mfma_f32_16x16x32_bf16 v[76:79], v[116:119], v[204:207], v[76:79]
	v_mfma_f32_16x16x32_bf16 v[72:75], v[128:131], v[204:207], v[72:75]
	v_mfma_f32_16x16x32_bf16 v[132:135], v[136:139], v[160:163], v[132:135]
	v_mfma_f32_16x16x32_bf16 v[124:127], v[144:147], v[160:163], v[124:127]
	v_mfma_f32_16x16x32_bf16 v[100:103], v[136:139], v[168:171], v[100:103]
	v_mfma_f32_16x16x32_bf16 v[96:99], v[144:147], v[168:171], v[96:99]
	v_mfma_f32_16x16x32_bf16 v[84:87], v[136:139], v[176:179], v[84:87]
	v_mfma_f32_16x16x32_bf16 v[80:83], v[144:147], v[176:179], v[80:83]
	v_mfma_f32_16x16x32_bf16 v[68:71], v[136:139], v[184:187], v[68:71]
	v_mfma_f32_16x16x32_bf16 v[64:67], v[144:147], v[184:187], v[64:67]
	v_mfma_f32_16x16x32_bf16 v[132:135], v[140:143], v[164:167], v[132:135]
	v_mfma_f32_16x16x32_bf16 v[124:127], v[156:159], v[164:167], v[124:127]
	v_mfma_f32_16x16x32_bf16 v[100:103], v[140:143], v[172:175], v[100:103]
	v_mfma_f32_16x16x32_bf16 v[96:99], v[156:159], v[172:175], v[96:99]
	v_mfma_f32_16x16x32_bf16 v[84:87], v[140:143], v[180:183], v[84:87]
	v_mfma_f32_16x16x32_bf16 v[80:83], v[156:159], v[180:183], v[80:83]
	v_mfma_f32_16x16x32_bf16 v[68:71], v[140:143], v[204:207], v[68:71]
	v_mfma_f32_16x16x32_bf16 v[64:67], v[156:159], v[204:207], v[64:67]
	s_setprio 0
	s_barrier
	s_add_i32 s16, s71, s30
	v_lshl_add_u64 v[208:209], s[20:21], 0, v[200:201]
	s_mov_b32 m0, s16
	ds_read_b128 v[160:163], v226 offset:16384
	ds_read_b128 v[164:167], v226 offset:17408
	ds_read_b128 v[168:171], v226 offset:18432
	ds_read_b128 v[172:175], v226 offset:19456
	ds_read_b128 v[176:179], v226 offset:20480
	ds_read_b128 v[180:183], v226 offset:21504
	ds_read_b128 v[184:187], v226 offset:22528
	ds_read_b128 v[204:207], v226 offset:23552
	global_load_lds_dwordx4 v[208:209], off
	s_add_i32 m0, s16, 0x2000
	s_add_u32 s16, s20, 0x160000
	v_lshl_add_u64 v[210:211], s[20:21], 0, v[192:193]
	s_addc_u32 s17, s21, 0
	s_add_i32 s71, s72, s30
	global_load_lds_dwordx4 v[210:211], off
	v_lshl_add_u64 v[212:213], s[16:17], 0, v[200:201]
	s_mov_b32 m0, s71
	v_lshl_add_u64 v[214:215], s[22:23], 0, v[190:191]
	global_load_lds_dwordx4 v[212:213], off
	v_lshl_add_u64 v[212:213], s[16:17], 0, v[192:193]
	s_add_i32 m0, s71, 0x2000
	s_nop 0
	global_load_lds_dwordx4 v[212:213], off
	v_lshl_add_u64 v[212:213], s[22:23], 0, v[188:189]
	s_mov_b32 m0, s31
	s_nop 0
	global_load_lds_dwordx4 v[212:213], off
	s_mov_b32 m0, s34
	s_nop 0
	global_load_lds_dwordx4 v[214:215], off
	s_waitcnt vmcnt(8)
	s_waitcnt lgkmcnt(0)
	s_barrier
; #define PG8_STAGE(bufoff, gbase, voff) do { _Pragma("unroll") for (int _i = 0; _i < 2; ++_i) \
;         __builtin_amdgcn_global_load_lds((const unsigned*)((const char*)(gbase) + (voff)[_i]), (LAS unsigned*)(lds + (bufoff) + ldsw + _i * 8192), 16, 0, 0); } while (0)
; #define PG8_LDA(dst, b, h) do { _Pragma("unroll") for (int m = 0; m < 4; ++m) _Pragma("unroll") for (int k = 0; k < 2; ++k) dst[m][k] = *(const LAS bf16x8*)(lds + PG8_SA(b, h) + aoff + m * 2048 + k * 1024); } while (0)
; #define PG8_LDB(dst, b, h) do { _Pragma("unroll") for (int n = 0; n < 2; ++n) _Pragma("unroll") for (int k = 0; k < 2; ++k) dst[n][k] = *(const LAS bf16x8*)(lds + PG8_SB(b, h) + boff + n * 2048 + k * 1024); } while (0)
; #define PG8_MMA(ai, bj, At, Bt) do { __builtin_amdgcn_s_setprio(1); _Pragma("unroll") for (int m = 0; m < 4; ++m) _Pragma("unroll") for (int n = 0; n < 2; ++n) _Pragma("unroll") for (int k = 0; k < 2; ++k) \
;         acc[ai][bj][m][n] = __builtin_amdgcn_mfma_f32_16x16x32_bf16(Bt[n][k], At[m][k], acc[ai][bj][m][n], 0, 0, 0); __builtin_amdgcn_s_setprio(0); } while (0)
; #define PG8_WAIT_V(n) asm volatile("s_waitcnt vmcnt(" #n ")" ::: "memory")
; #define PG8_WAIT_L(n) asm volatile("s_waitcnt lgkmcnt(" #n ")" ::: "memory")
; #define PG8_BAR __builtin_amdgcn_s_barrier()
; #define PG8_SCHED __builtin_amdgcn_sched_barrier(0)
; template <class Epi, class Sched, bool APERM = false, bool HALFN = false>
; __device__ __forceinline__ void gemm_phase(LAS unsigned char* lds, const int tid_in, const int K, const Sched& S, const Epi& E) {
;     ...
;             PG8_WAIT_V(8); PG8_WAIT_L(0); PG8_BAR; PG8_MMA(1, 0, At, B0); if constexpr (!HALFN) PG8_MMA(1, 1, At, B1); PG8_BAR; PG8_SCHED;
;             PG8_LDB(B0, 1, 0); PG8_LDB(B1, 1, 1); PG8_SCHED; PG8_LDA(At, 1, 0); PG8_STAGE(PG8_SA(0, 1), a2 + hstepA, voffA);
;             PG8_WAIT_V(8); PG8_WAIT_L(0); PG8_BAR; PG8_MMA(0, 0, At, B0); if constexpr (!HALFN) PG8_MMA(0, 1, At, B1); PG8_BAR; PG8_SCHED;
;             PG8_LDA(At, 1, 1); PG8_STAGE(PG8_SB(1, 0), b3, voffB); PG8_STAGE(PG8_SB(1, 1), b3 + hstep, voffB); PG8_STAGE(PG8_SA(1, 0), a3, voffA);
	s_setprio 1
	s_waitcnt lgkmcnt(0)
	v_mfma_f32_16x16x32_bf16 v[60:63], v[112:115], v[160:163], v[60:63]
	v_mfma_f32_16x16x32_bf16 v[56:59], v[120:123], v[160:163], v[56:59]
	v_mfma_f32_16x16x32_bf16 v[44:47], v[112:115], v[168:171], v[44:47]
	v_mfma_f32_16x16x32_bf16 v[40:43], v[120:123], v[168:171], v[40:43]
	v_mfma_f32_16x16x32_bf16 v[28:31], v[112:115], v[176:179], v[28:31]
	v_mfma_f32_16x16x32_bf16 v[24:27], v[120:123], v[176:179], v[24:27]
	v_mfma_f32_16x16x32_bf16 v[12:15], v[112:115], v[184:187], v[12:15]
	v_mfma_f32_16x16x32_bf16 v[8:11], v[120:123], v[184:187], v[8:11]
	v_mfma_f32_16x16x32_bf16 v[60:63], v[116:119], v[164:167], v[60:63]
	v_mfma_f32_16x16x32_bf16 v[56:59], v[128:131], v[164:167], v[56:59]
	v_mfma_f32_16x16x32_bf16 v[44:47], v[116:119], v[172:175], v[44:47]
	v_mfma_f32_16x16x32_bf16 v[40:43], v[128:131], v[172:175], v[40:43]
	v_mfma_f32_16x16x32_bf16 v[28:31], v[116:119], v[180:183], v[28:31]
	v_mfma_f32_16x16x32_bf16 v[24:27], v[128:131], v[180:183], v[24:27]
	v_mfma_f32_16x16x32_bf16 v[12:15], v[116:119], v[204:207], v[12:15]
	v_mfma_f32_16x16x32_bf16 v[8:11], v[128:131], v[204:207], v[8:11]
	v_mfma_f32_16x16x32_bf16 v[52:55], v[136:139], v[160:163], v[52:55]
	v_mfma_f32_16x16x32_bf16 v[48:51], v[144:147], v[160:163], v[48:51]
	v_mfma_f32_16x16x32_bf16 v[36:39], v[136:139], v[168:171], v[36:39]
	v_mfma_f32_16x16x32_bf16 v[32:35], v[144:147], v[168:171], v[32:35]
	v_mfma_f32_16x16x32_bf16 v[20:23], v[136:139], v[176:179], v[20:23]
	v_mfma_f32_16x16x32_bf16 v[16:19], v[144:147], v[176:179], v[16:19]
	v_mfma_f32_16x16x32_bf16 v[4:7], v[136:139], v[184:187], v[4:7]
	v_mfma_f32_16x16x32_bf16 v[0:3], v[144:147], v[184:187], v[0:3]
	v_mfma_f32_16x16x32_bf16 v[52:55], v[140:143], v[164:167], v[52:55]
	v_mfma_f32_16x16x32_bf16 v[48:51], v[156:159], v[164:167], v[48:51]
	v_mfma_f32_16x16x32_bf16 v[36:39], v[140:143], v[172:175], v[36:39]
	v_mfma_f32_16x16x32_bf16 v[32:35], v[156:159], v[172:175], v[32:35]
	v_mfma_f32_16x16x32_bf16 v[20:23], v[140:143], v[180:183], v[20:23]
	v_mfma_f32_16x16x32_bf16 v[16:19], v[156:159], v[180:183], v[16:19]
	v_mfma_f32_16x16x32_bf16 v[4:7], v[140:143], v[204:207], v[4:7]
	v_mfma_f32_16x16x32_bf16 v[0:3], v[156:159], v[204:207], v[0:3]
	s_setprio 0
	s_barrier
	s_add_i32 s71, 0, 0x18000
	s_add_i32 s72, 0, 0x1c000
	v_add_u32_e32 v128, s71, v220
	v_add_u32_e32 v156, s72, v220
	ds_read_b128 v[112:115], v128
	ds_read_b128 v[116:119], v128 offset:1024
	ds_read_b128 v[120:123], v128 offset:2048
	ds_read_b128 v[128:131], v128 offset:3072
	ds_read_b128 v[136:139], v156
	ds_read_b128 v[140:143], v156 offset:1024
	ds_read_b128 v[144:147], v156 offset:2048
	ds_read_b128 v[156:159], v156 offset:3072
	s_add_u32 s16, s22, 0x160000
	s_addc_u32 s17, s23, 0
	s_mov_b32 m0, s35
	v_lshl_add_u64 v[216:217], s[16:17], 0, v[188:189]
	ds_read_b128 v[160:163], v226 offset:32768
	ds_read_b128 v[164:167], v226 offset:33792
	ds_read_b128 v[168:171], v226 offset:34816
	ds_read_b128 v[172:175], v226 offset:35840
	ds_read_b128 v[176:179], v226 offset:36864
	ds_read_b128 v[180:183], v226 offset:37888
	ds_read_b128 v[184:187], v226 offset:38912
	ds_read_b128 v[204:207], v226 offset:39936
	global_load_lds_dwordx4 v[216:217], off
	v_lshl_add_u64 v[216:217], s[16:17], 0, v[190:191]
	s_mov_b32 m0, s38
	s_nop 0
	global_load_lds_dwordx4 v[216:217], off
	s_waitcnt vmcnt(8)
	s_waitcnt lgkmcnt(0)
	s_barrier
	s_setprio 1
	s_waitcnt lgkmcnt(0)
	v_mfma_f32_16x16x32_bf16 v[152:155], v[112:115], v[160:163], v[152:155]
	v_mfma_f32_16x16x32_bf16 v[148:151], v[120:123], v[160:163], v[148:151]
	v_mfma_f32_16x16x32_bf16 v[108:111], v[112:115], v[168:171], v[108:111]
	v_mfma_f32_16x16x32_bf16 v[104:107], v[120:123], v[168:171], v[104:107]
	v_mfma_f32_16x16x32_bf16 v[92:95], v[112:115], v[176:179], v[92:95]
	v_mfma_f32_16x16x32_bf16 v[88:91], v[120:123], v[176:179], v[88:91]
	v_mfma_f32_16x16x32_bf16 v[76:79], v[112:115], v[184:187], v[76:79]
	v_mfma_f32_16x16x32_bf16 v[72:75], v[120:123], v[184:187], v[72:75]
	v_mfma_f32_16x16x32_bf16 v[152:155], v[116:119], v[164:167], v[152:155]
	v_mfma_f32_16x16x32_bf16 v[148:151], v[128:131], v[164:167], v[148:151]
	v_mfma_f32_16x16x32_bf16 v[108:111], v[116:119], v[172:175], v[108:111]
	v_mfma_f32_16x16x32_bf16 v[104:107], v[128:131], v[172:175], v[104:107]
	v_mfma_f32_16x16x32_bf16 v[92:95], v[116:119], v[180:183], v[92:95]
	v_mfma_f32_16x16x32_bf16 v[88:91], v[128:131], v[180:183], v[88:91]
	v_mfma_f32_16x16x32_bf16 v[76:79], v[116:119], v[204:207], v[76:79]
	v_mfma_f32_16x16x32_bf16 v[72:75], v[128:131], v[204:207], v[72:75]
	v_mfma_f32_16x16x32_bf16 v[132:135], v[136:139], v[160:163], v[132:135]
	v_mfma_f32_16x16x32_bf16 v[124:127], v[144:147], v[160:163], v[124:127]
	v_mfma_f32_16x16x32_bf16 v[100:103], v[136:139], v[168:171], v[100:103]
	v_mfma_f32_16x16x32_bf16 v[96:99], v[144:147], v[168:171], v[96:99]
	v_mfma_f32_16x16x32_bf16 v[84:87], v[136:139], v[176:179], v[84:87]
	v_mfma_f32_16x16x32_bf16 v[80:83], v[144:147], v[176:179], v[80:83]
	v_mfma_f32_16x16x32_bf16 v[68:71], v[136:139], v[184:187], v[68:71]
	v_mfma_f32_16x16x32_bf16 v[64:67], v[144:147], v[184:187], v[64:67]
	v_mfma_f32_16x16x32_bf16 v[132:135], v[140:143], v[164:167], v[132:135]
	v_mfma_f32_16x16x32_bf16 v[124:127], v[156:159], v[164:167], v[124:127]
	v_mfma_f32_16x16x32_bf16 v[100:103], v[140:143], v[172:175], v[100:103]
	v_mfma_f32_16x16x32_bf16 v[96:99], v[156:159], v[172:175], v[96:99]
	v_mfma_f32_16x16x32_bf16 v[84:87], v[140:143], v[180:183], v[84:87]
	v_mfma_f32_16x16x32_bf16 v[80:83], v[156:159], v[180:183], v[80:83]
	v_mfma_f32_16x16x32_bf16 v[68:71], v[140:143], v[204:207], v[68:71]
	v_mfma_f32_16x16x32_bf16 v[64:67], v[156:159], v[204:207], v[64:67]
	s_setprio 0
	s_barrier
; #define PG8_STAGE(bufoff, gbase, voff) do { _Pragma("unroll") for (int _i = 0; _i < 2; ++_i) \
;         __builtin_amdgcn_global_load_lds((const unsigned*)((const char*)(gbase) + (voff)[_i]), (LAS unsigned*)(lds + (bufoff) + ldsw + _i * 8192), 16, 0, 0); } while (0)
; #define PG8_LDA(dst, b, h) do { _Pragma("unroll") for (int m = 0; m < 4; ++m) _Pragma("unroll") for (int k = 0; k < 2; ++k) dst[m][k] = *(const LAS bf16x8*)(lds + PG8_SA(b, h) + aoff + m * 2048 + k * 1024); } while (0)
; #define PG8_MMA(ai, bj, At, Bt) do { __builtin_amdgcn_s_setprio(1); _Pragma("unroll") for (int m = 0; m < 4; ++m) _Pragma("unroll") for (int n = 0; n < 2; ++n) _Pragma("unroll") for (int k = 0; k < 2; ++k) \
;         acc[ai][bj][m][n] = __builtin_amdgcn_mfma_f32_16x16x32_bf16(Bt[n][k], At[m][k], acc[ai][bj][m][n], 0, 0, 0); __builtin_amdgcn_s_setprio(0); } while (0)
; #define PG8_WAIT_V(n) asm volatile("s_waitcnt vmcnt(" #n ")" ::: "memory")
; #define PG8_WAIT_L(n) asm volatile("s_waitcnt lgkmcnt(" #n ")" ::: "memory")
; #define PG8_BAR __builtin_amdgcn_s_barrier()
; #define PG8_SCHED __builtin_amdgcn_sched_barrier(0)
; template <class Epi, class Sched, bool APERM = false, bool HALFN = false>
; __device__ __forceinline__ void gemm_phase(LAS unsigned char* lds, const int tid_in, const int K, const Sched& S, const Epi& E) {
;     ...
;             PG8_LDA(At, 1, 1); PG8_STAGE(PG8_SB(1, 0), b3, voffB); PG8_STAGE(PG8_SB(1, 1), b3 + hstep, voffB); PG8_STAGE(PG8_SA(1, 0), a3, voffA);
;             PG8_WAIT_V(8); PG8_WAIT_L(0); PG8_BAR; PG8_MMA(1, 0, At, B0); if constexpr (!HALFN) PG8_MMA(1, 1, At, B1); PG8_BAR; PG8_SCHED;
;         }
	s_add_i32 s16, s71, s30
	v_lshl_add_u64 v[208:209], v[208:209], 0, s[78:79]
	s_mov_b32 m0, s16
	ds_read_b128 v[160:163], v226 offset:49152
	ds_read_b128 v[164:167], v226 offset:50176
	ds_read_b128 v[168:171], v226 offset:51200
	ds_read_b128 v[172:175], v226 offset:52224
	ds_read_b128 v[176:179], v226 offset:53248
	ds_read_b128 v[180:183], v226 offset:54272
	ds_read_b128 v[184:187], v226 offset:55296
	ds_read_b128 v[204:207], v226 offset:56320
	global_load_lds_dwordx4 v[208:209], off
	s_add_i32 m0, s16, 0x2000
	s_add_u32 s16, s20, 0x160080
	v_lshl_add_u64 v[208:209], v[210:211], 0, s[78:79]
	s_addc_u32 s17, s21, 0
	s_add_i32 s20, s72, s30
	global_load_lds_dwordx4 v[208:209], off
	v_lshl_add_u64 v[208:209], s[16:17], 0, v[200:201]
	s_mov_b32 m0, s20
	s_nop 0
	global_load_lds_dwordx4 v[208:209], off
	v_lshl_add_u64 v[208:209], s[16:17], 0, v[192:193]
	s_add_i32 m0, s20, 0x2000
	s_nop 0
	global_load_lds_dwordx4 v[208:209], off
	v_lshl_add_u64 v[208:209], v[212:213], 0, s[78:79]
	s_mov_b32 m0, s39
	s_nop 0
	global_load_lds_dwordx4 v[208:209], off
	v_lshl_add_u64 v[208:209], v[214:215], 0, s[78:79]
	s_mov_b32 m0, s44
	s_nop 0
	global_load_lds_dwordx4 v[208:209], off
	s_waitcnt vmcnt(8)
	s_waitcnt lgkmcnt(0)
	s_barrier
	s_setprio 1
	s_waitcnt lgkmcnt(0)
	v_mfma_f32_16x16x32_bf16 v[60:63], v[112:115], v[160:163], v[60:63]
	v_mfma_f32_16x16x32_bf16 v[56:59], v[120:123], v[160:163], v[56:59]
	v_mfma_f32_16x16x32_bf16 v[44:47], v[112:115], v[168:171], v[44:47]
	v_mfma_f32_16x16x32_bf16 v[40:43], v[120:123], v[168:171], v[40:43]
	v_mfma_f32_16x16x32_bf16 v[28:31], v[112:115], v[176:179], v[28:31]
	v_mfma_f32_16x16x32_bf16 v[24:27], v[120:123], v[176:179], v[24:27]
	v_mfma_f32_16x16x32_bf16 v[12:15], v[112:115], v[184:187], v[12:15]
	v_mfma_f32_16x16x32_bf16 v[8:11], v[120:123], v[184:187], v[8:11]
	v_mfma_f32_16x16x32_bf16 v[60:63], v[116:119], v[164:167], v[60:63]
	v_mfma_f32_16x16x32_bf16 v[56:59], v[128:131], v[164:167], v[56:59]
	v_mfma_f32_16x16x32_bf16 v[44:47], v[116:119], v[172:175], v[44:47]
	v_mfma_f32_16x16x32_bf16 v[40:43], v[128:131], v[172:175], v[40:43]
	v_mfma_f32_16x16x32_bf16 v[28:31], v[116:119], v[180:183], v[28:31]
	v_mfma_f32_16x16x32_bf16 v[24:27], v[128:131], v[180:183], v[24:27]
	v_mfma_f32_16x16x32_bf16 v[12:15], v[116:119], v[204:207], v[12:15]
	v_mfma_f32_16x16x32_bf16 v[8:11], v[128:131], v[204:207], v[8:11]
	v_mfma_f32_16x16x32_bf16 v[52:55], v[136:139], v[160:163], v[52:55]
	v_mfma_f32_16x16x32_bf16 v[48:51], v[144:147], v[160:163], v[48:51]
	v_mfma_f32_16x16x32_bf16 v[36:39], v[136:139], v[168:171], v[36:39]
	v_mfma_f32_16x16x32_bf16 v[32:35], v[144:147], v[168:171], v[32:35]
	v_mfma_f32_16x16x32_bf16 v[20:23], v[136:139], v[176:179], v[20:23]
	v_mfma_f32_16x16x32_bf16 v[16:19], v[144:147], v[176:179], v[16:19]
	v_mfma_f32_16x16x32_bf16 v[4:7], v[136:139], v[184:187], v[4:7]
	v_mfma_f32_16x16x32_bf16 v[0:3], v[144:147], v[184:187], v[0:3]
	v_mfma_f32_16x16x32_bf16 v[52:55], v[140:143], v[164:167], v[52:55]
	v_mfma_f32_16x16x32_bf16 v[48:51], v[156:159], v[164:167], v[48:51]
	v_mfma_f32_16x16x32_bf16 v[36:39], v[140:143], v[172:175], v[36:39]
	v_mfma_f32_16x16x32_bf16 v[32:35], v[156:159], v[172:175], v[32:35]
	v_mfma_f32_16x16x32_bf16 v[20:23], v[140:143], v[180:183], v[20:23]
	v_mfma_f32_16x16x32_bf16 v[16:19], v[156:159], v[180:183], v[16:19]
	v_mfma_f32_16x16x32_bf16 v[4:7], v[140:143], v[204:207], v[4:7]
	v_mfma_f32_16x16x32_bf16 v[0:3], v[156:159], v[204:207], v[0:3]
	s_setprio 0
	s_barrier
	s_add_i32 s70, s70, 2
	s_add_u32 s53, s53, 0x100
	s_addc_u32 s57, s57, 0
	s_cmpk_gt_u32 s70, 0x55
	s_mov_b64 s[16:17], s[18:19]
	s_cbranch_scc0 .LBB0_1033
	s_and_b64 vcc, exec, s[8:9]
	s_cbranch_vccz .LBB0_1036
	s_barrier
